# GEMM K-loops: no per-segment setprio toggling, one static priority raise for waves 0-3 (reset after each phase)
# speedup vs baseline: 1.0064x; 1.0009x over previous
; #define PG8_STAGE(bufoff, gbase, voff) do { _Pragma("unroll") for (int _i = 0; _i < 2; ++_i) \
;         __builtin_amdgcn_global_load_lds((const unsigned*)((const char*)(gbase) + (voff)[_i]), (PG8_LAS unsigned*)(lds + (bufoff) + ldsw + _i * 8192), 16, 0, 0); } while (0)
; #define PG8_LDA(dst, b, h) do { _Pragma("unroll") for (int m = 0; m < 4; ++m) _Pragma("unroll") for (int k = 0; k < 2; ++k) dst[m][k] = *(const PG8_LAS bf16x8*)(lds + PG8_SA(b, h) + aoff + m * 2048 + k * 1024); } while (0)
; #define PG8_LDB(dst, b, h) do { _Pragma("unroll") for (int n = 0; n < 2; ++n) _Pragma("unroll") for (int k = 0; k < 2; ++k) dst[n][k] = *(const PG8_LAS bf16x8*)(lds + PG8_SB(b, h) + boff + n * 2048 + k * 1024); } while (0)
; #define PG8_WAIT_V(n) asm volatile("s_waitcnt vmcnt(" #n ")" ::: "memory")
; #define PG8_WAIT_L(n) asm volatile("s_waitcnt lgkmcnt(" #n ")" ::: "memory")
; #define PG8_BAR __builtin_amdgcn_s_barrier()
; #define PG8_SCHED __builtin_amdgcn_sched_barrier(0)
; template <class Epi, class Sched, bool ALIGN_EPI = false, bool SP2 = false>
; __device__ __forceinline__ void gemm_phase(PG8_LAS unsigned char* lds, const Gemm g, const Sched& S, const Epi& E) {
;     ...
;         const char* nA = has_next ? (const char*)g.A + (size_t)nxt.pm * tstep : cA; const char* nB = has_next ? (const char*)g.Bt + (size_t)nxt.pn * tstep : cB;
;         for (int t = 0; t < nt; t += 2) {
;             const bool last = (t == nt - 2);
;             const char* a1 = cA + (size_t)(t + 1) * kstep;
;             const char* a2 = last ? nA : cA + (size_t)(t + 2) * kstep; const char* b2 = last ? nB : cB + (size_t)(t + 2) * kstep;
;             const char* a3 = a2 + kstep; const char* b3 = b2 + kstep;
;             if (last && has_next) S.a_ready(nxt);
;             if constexpr (SP2) {
;             PG8_LDB(B0, 0, 0); PG8_LDB(B1, 0, 1); PG8_SCHED; PG8_LDA(At, 0, 0); PG8_STAGE(PG8_SA(1, 1), a1 + hstep, voffA);
;             PG8_WAIT_V(8); PG8_WAIT_L(0); PG8_BAR; PG8_MMA(0, 0, At, B0); PG8_MMA(0, 1, At, B1); PG8_BAR; PG8_SCHED;
;             PG8_LDA(At, 0, 1); PG8_STAGE(PG8_SB(0, 0), b2, voffB); PG8_STAGE(PG8_SB(0, 1), b2 + hstep, voffB); PG8_STAGE(PG8_SA(0, 0), a2, voffA);
;             PG8_WAIT_V(8); PG8_WAIT_L(0); PG8_BAR; PG8_MMA(1, 0, At, B0); PG8_MMA(1, 1, At, B1); PG8_BAR; PG8_SCHED;
.LBB0_766:
	s_ashr_i32 s17, s16, 31
	s_lshl_b64 s[20:21], s[16:17], 19
	s_add_u32 s20, s77, s20
	s_addc_u32 s21, s26, s21
	s_and_b64 s[30:31], s[6:7], exec
	s_cselect_b32 s17, s21, s39
	s_cselect_b32 s48, s20, s38
	s_ashr_i32 s15, s14, 31
	s_lshl_b64 s[30:31], s[14:15], 19
	v_readlane_b32 s42, v255, 18
	v_readlane_b32 s43, v255, 19
	s_add_u32 s30, s42, s30
	s_addc_u32 s31, s43, s31
	s_and_b64 s[42:43], s[6:7], exec
	s_cselect_b32 s15, s31, s41
	s_cselect_b32 s49, s30, s40
	s_add_u32 s38, s38, 0x40080
	s_addc_u32 s39, s39, 0
	s_add_u32 s50, s40, 0x100
	s_addc_u32 s51, s41, 0
	s_mov_b32 s54, -2
	s_add_u32 s40, s38, 0xfffc0080
	s_addc_u32 s41, s39, -1
	s_add_i32 s55, 0, 0x10000
	s_cmp_eq_u32 s54, 12
	s_cselect_b32 s43, s17, s41
	s_cselect_b32 s42, s48, s40
	v_add_u32_e32 v140, s55, v143
	s_cselect_b32 s41, s15, s51
	s_cselect_b32 s40, s49, s50
	s_add_i32 s63, 0, 0x14000
	ds_read_b128 v[146:149], v140
	ds_read_b128 v[150:153], v140 offset:1024
	ds_read_b128 v[154:157], v140 offset:2048
	ds_read_b128 v[158:161], v140 offset:3072
	v_add_u32_e32 v140, s63, v143
	ds_read_b128 v[162:165], v140
	ds_read_b128 v[166:169], v140 offset:1024
	ds_read_b128 v[170:173], v140 offset:2048
	ds_read_b128 v[174:177], v140 offset:3072
	v_lshl_add_u64 v[140:141], s[38:39], 0, v[136:137]
	s_add_i32 m0, s19, 0xc000
	ds_read_b128 v[178:181], v145
	ds_read_b128 v[182:185], v145 offset:1024
	ds_read_b128 v[186:189], v145 offset:2048
	ds_read_b128 v[190:193], v145 offset:3072
	ds_read_b128 v[198:201], v145 offset:4096
	ds_read_b128 v[202:205], v145 offset:5120
	ds_read_b128 v[206:209], v145 offset:6144
	ds_read_b128 v[210:213], v145 offset:7168
	global_load_lds_dwordx4 v[140:141], off
	v_lshl_add_u64 v[140:141], s[38:39], 0, v[138:139]
	s_add_i32 m0, s19, 0xe000
	s_nop 0
	global_load_lds_dwordx4 v[140:141], off
	s_waitcnt vmcnt(8)
	s_waitcnt lgkmcnt(0)
	s_barrier
	s_waitcnt lgkmcnt(0)
	v_mfma_f32_16x16x32_bf16 v[126:129], v[146:149], v[178:181], 0
	v_mfma_f32_16x16x32_bf16 v[122:125], v[154:157], v[178:181], 0
	v_mfma_f32_16x16x32_bf16 v[118:121], v[146:149], v[186:189], 0
	v_mfma_f32_16x16x32_bf16 v[110:113], v[154:157], v[186:189], 0
	v_mfma_f32_16x16x32_bf16 v[102:105], v[146:149], v[198:201], 0
	v_mfma_f32_16x16x32_bf16 v[94:97], v[154:157], v[198:201], 0
	v_mfma_f32_16x16x32_bf16 v[86:89], v[146:149], v[206:209], 0
	v_mfma_f32_16x16x32_bf16 v[78:81], v[154:157], v[206:209], 0
	v_mfma_f32_16x16x32_bf16 v[126:129], v[150:153], v[182:185], v[126:129]
	v_mfma_f32_16x16x32_bf16 v[122:125], v[158:161], v[182:185], v[122:125]
	v_mfma_f32_16x16x32_bf16 v[118:121], v[150:153], v[190:193], v[118:121]
	v_mfma_f32_16x16x32_bf16 v[110:113], v[158:161], v[190:193], v[110:113]
	v_mfma_f32_16x16x32_bf16 v[102:105], v[150:153], v[202:205], v[102:105]
	v_mfma_f32_16x16x32_bf16 v[94:97], v[158:161], v[202:205], v[94:97]
	v_mfma_f32_16x16x32_bf16 v[86:89], v[150:153], v[210:213], v[86:89]
	v_mfma_f32_16x16x32_bf16 v[78:81], v[158:161], v[210:213], v[78:81]
	v_mfma_f32_16x16x32_bf16 v[114:117], v[162:165], v[178:181], 0
	v_mfma_f32_16x16x32_bf16 v[106:109], v[170:173], v[178:181], 0
	v_mfma_f32_16x16x32_bf16 v[98:101], v[162:165], v[186:189], 0
	v_mfma_f32_16x16x32_bf16 v[90:93], v[170:173], v[186:189], 0
	v_mfma_f32_16x16x32_bf16 v[82:85], v[162:165], v[198:201], 0
	v_mfma_f32_16x16x32_bf16 v[74:77], v[170:173], v[198:201], 0
	v_mfma_f32_16x16x32_bf16 v[70:73], v[162:165], v[206:209], 0
	v_mfma_f32_16x16x32_bf16 v[66:69], v[170:173], v[206:209], 0
	v_mfma_f32_16x16x32_bf16 v[114:117], v[166:169], v[182:185], v[114:117]
	v_mfma_f32_16x16x32_bf16 v[106:109], v[174:177], v[182:185], v[106:109]
	v_mfma_f32_16x16x32_bf16 v[98:101], v[166:169], v[190:193], v[98:101]
	v_mfma_f32_16x16x32_bf16 v[90:93], v[174:177], v[190:193], v[90:93]
	v_mfma_f32_16x16x32_bf16 v[82:85], v[166:169], v[202:205], v[82:85]
	v_mfma_f32_16x16x32_bf16 v[74:77], v[174:177], v[202:205], v[74:77]
	v_mfma_f32_16x16x32_bf16 v[70:73], v[166:169], v[210:213], v[70:73]
	v_mfma_f32_16x16x32_bf16 v[66:69], v[174:177], v[210:213], v[66:69]
	s_barrier
	s_add_i32 s55, s55, s5
	v_lshl_add_u64 v[140:141], s[40:41], 0, v[0:1]
	s_mov_b32 m0, s55
	ds_read_b128 v[178:181], v145 offset:16384
	ds_read_b128 v[182:185], v145 offset:17408
	ds_read_b128 v[186:189], v145 offset:18432
	ds_read_b128 v[190:193], v145 offset:19456
	ds_read_b128 v[198:201], v145 offset:20480
	ds_read_b128 v[202:205], v145 offset:21504
	ds_read_b128 v[206:209], v145 offset:22528
	ds_read_b128 v[210:213], v145 offset:23552
	global_load_lds_dwordx4 v[140:141], off
	s_add_i32 m0, s55, 0x2000
	s_add_u32 s72, s40, 0x40000
	v_lshl_add_u64 v[214:215], s[40:41], 0, v[130:131]
	s_addc_u32 s73, s41, 0
	s_add_i32 s55, s63, s5
	global_load_lds_dwordx4 v[214:215], off
	v_lshl_add_u64 v[216:217], s[72:73], 0, v[0:1]
	s_mov_b32 m0, s55
	v_lshl_add_u64 v[218:219], s[42:43], 0, v[132:133]
	global_load_lds_dwordx4 v[216:217], off
	v_lshl_add_u64 v[216:217], s[72:73], 0, v[130:131]
	s_add_i32 m0, s55, 0x2000
	s_nop 0
	global_load_lds_dwordx4 v[216:217], off
	v_lshl_add_u64 v[216:217], s[42:43], 0, v[134:135]
	s_mov_b32 m0, s19
	s_nop 0
	global_load_lds_dwordx4 v[216:217], off
	s_mov_b32 m0, s27
	s_nop 0
	global_load_lds_dwordx4 v[218:219], off
	s_waitcnt vmcnt(8)
	s_waitcnt lgkmcnt(0)
	s_barrier
; #define PG8_STAGE(bufoff, gbase, voff) do { _Pragma("unroll") for (int _i = 0; _i < 2; ++_i) \
;         __builtin_amdgcn_global_load_lds((const unsigned*)((const char*)(gbase) + (voff)[_i]), (PG8_LAS unsigned*)(lds + (bufoff) + ldsw + _i * 8192), 16, 0, 0); } while (0)
; #define PG8_LDA(dst, b, h) do { _Pragma("unroll") for (int m = 0; m < 4; ++m) _Pragma("unroll") for (int k = 0; k < 2; ++k) dst[m][k] = *(const PG8_LAS bf16x8*)(lds + PG8_SA(b, h) + aoff + m * 2048 + k * 1024); } while (0)
; #define PG8_LDB(dst, b, h) do { _Pragma("unroll") for (int n = 0; n < 2; ++n) _Pragma("unroll") for (int k = 0; k < 2; ++k) dst[n][k] = *(const PG8_LAS bf16x8*)(lds + PG8_SB(b, h) + boff + n * 2048 + k * 1024); } while (0)
; #define PG8_MMA(ai, bj, At, Bt) do { __builtin_amdgcn_s_setprio(1); _Pragma("unroll") for (int m = 0; m < 4; ++m) _Pragma("unroll") for (int n = 0; n < 2; ++n) _Pragma("unroll") for (int k = 0; k < 2; ++k) \
;         acc[ai][bj][m][n] = __builtin_amdgcn_mfma_f32_16x16x32_bf16(Bt[n][k], At[m][k], acc[ai][bj][m][n], 0, 0, 0); __builtin_amdgcn_s_setprio(0); } while (0)
; #define PG8_WAIT_V(n) asm volatile("s_waitcnt vmcnt(" #n ")" ::: "memory")
; #define PG8_WAIT_L(n) asm volatile("s_waitcnt lgkmcnt(" #n ")" ::: "memory")
; #define PG8_BAR __builtin_amdgcn_s_barrier()
; #define PG8_SCHED __builtin_amdgcn_sched_barrier(0)
; template <class Epi, class Sched, bool ALIGN_EPI = false, bool SP2 = false>
; __device__ __forceinline__ void gemm_phase(PG8_LAS unsigned char* lds, const Gemm g, const Sched& S, const Epi& E) {
;     ...
;             PG8_WAIT_V(8); PG8_WAIT_L(0); PG8_BAR; PG8_MMA(1, 0, At, B0); PG8_MMA(1, 1, At, B1); PG8_BAR; PG8_SCHED;
;             PG8_LDB(B0, 1, 0); PG8_LDB(B1, 1, 1); PG8_SCHED; PG8_LDA(At, 1, 0); PG8_STAGE(PG8_SA(0, 1), a2 + hstep, voffA);
;             PG8_WAIT_V(8); PG8_WAIT_L(0); PG8_BAR; PG8_MMA(0, 0, At, B0); PG8_MMA(0, 1, At, B1); PG8_BAR; PG8_SCHED;
;             PG8_LDA(At, 1, 1); PG8_STAGE(PG8_SB(1, 0), b3, voffB); PG8_STAGE(PG8_SB(1, 1), b3 + hstep, voffB); PG8_STAGE(PG8_SA(1, 0), a3, voffA);
;             PG8_WAIT_V(8); PG8_WAIT_L(0); PG8_BAR; PG8_MMA(1, 0, At, B0); PG8_MMA(1, 1, At, B1); PG8_BAR; PG8_SCHED;
	s_waitcnt lgkmcnt(0)
	v_mfma_f32_16x16x32_bf16 v[62:65], v[146:149], v[178:181], 0
	v_mfma_f32_16x16x32_bf16 v[58:61], v[154:157], v[178:181], 0
	v_mfma_f32_16x16x32_bf16 v[54:57], v[146:149], v[186:189], 0
	v_mfma_f32_16x16x32_bf16 v[46:49], v[154:157], v[186:189], 0
	v_mfma_f32_16x16x32_bf16 v[38:41], v[146:149], v[198:201], 0
	v_mfma_f32_16x16x32_bf16 v[30:33], v[154:157], v[198:201], 0
	v_mfma_f32_16x16x32_bf16 v[22:25], v[146:149], v[206:209], 0
	v_mfma_f32_16x16x32_bf16 v[14:17], v[154:157], v[206:209], 0
	v_mfma_f32_16x16x32_bf16 v[62:65], v[150:153], v[182:185], v[62:65]
	v_mfma_f32_16x16x32_bf16 v[58:61], v[158:161], v[182:185], v[58:61]
	v_mfma_f32_16x16x32_bf16 v[54:57], v[150:153], v[190:193], v[54:57]
	v_mfma_f32_16x16x32_bf16 v[46:49], v[158:161], v[190:193], v[46:49]
	v_mfma_f32_16x16x32_bf16 v[38:41], v[150:153], v[202:205], v[38:41]
	v_mfma_f32_16x16x32_bf16 v[30:33], v[158:161], v[202:205], v[30:33]
	v_mfma_f32_16x16x32_bf16 v[22:25], v[150:153], v[210:213], v[22:25]
	v_mfma_f32_16x16x32_bf16 v[14:17], v[158:161], v[210:213], v[14:17]
	v_mfma_f32_16x16x32_bf16 v[50:53], v[162:165], v[178:181], 0
	v_mfma_f32_16x16x32_bf16 v[42:45], v[170:173], v[178:181], 0
	v_mfma_f32_16x16x32_bf16 v[34:37], v[162:165], v[186:189], 0
	v_mfma_f32_16x16x32_bf16 v[26:29], v[170:173], v[186:189], 0
	v_mfma_f32_16x16x32_bf16 v[18:21], v[162:165], v[198:201], 0
	v_mfma_f32_16x16x32_bf16 v[10:13], v[170:173], v[198:201], 0
	v_mfma_f32_16x16x32_bf16 v[6:9], v[162:165], v[206:209], 0
	v_mfma_f32_16x16x32_bf16 v[2:5], v[170:173], v[206:209], 0
	v_mfma_f32_16x16x32_bf16 v[50:53], v[166:169], v[182:185], v[50:53]
	v_mfma_f32_16x16x32_bf16 v[42:45], v[174:177], v[182:185], v[42:45]
	v_mfma_f32_16x16x32_bf16 v[34:37], v[166:169], v[190:193], v[34:37]
	v_mfma_f32_16x16x32_bf16 v[26:29], v[174:177], v[190:193], v[26:29]
	v_mfma_f32_16x16x32_bf16 v[18:21], v[166:169], v[202:205], v[18:21]
	v_mfma_f32_16x16x32_bf16 v[10:13], v[174:177], v[202:205], v[10:13]
	v_mfma_f32_16x16x32_bf16 v[6:9], v[166:169], v[210:213], v[6:9]
	v_mfma_f32_16x16x32_bf16 v[2:5], v[174:177], v[210:213], v[2:5]
	s_barrier
	s_add_i32 s55, 0, 0x18000
	s_add_i32 s63, 0, 0x1c000
	v_add_u32_e32 v158, s55, v143
	v_add_u32_e32 v174, s63, v143
	ds_read_b128 v[146:149], v158
	ds_read_b128 v[150:153], v158 offset:1024
	ds_read_b128 v[154:157], v158 offset:2048
	ds_read_b128 v[158:161], v158 offset:3072
	ds_read_b128 v[162:165], v174
	ds_read_b128 v[166:169], v174 offset:1024
	ds_read_b128 v[170:173], v174 offset:2048
	ds_read_b128 v[174:177], v174 offset:3072
	s_add_u32 s42, s42, 0x40000
	s_addc_u32 s43, s43, 0
	s_mov_b32 m0, s28
	v_lshl_add_u64 v[220:221], s[42:43], 0, v[134:135]
	ds_read_b128 v[178:181], v145 offset:32768
	ds_read_b128 v[182:185], v145 offset:33792
	ds_read_b128 v[186:189], v145 offset:34816
	ds_read_b128 v[190:193], v145 offset:35840
	ds_read_b128 v[198:201], v145 offset:36864
	ds_read_b128 v[202:205], v145 offset:37888
	ds_read_b128 v[206:209], v145 offset:38912
	ds_read_b128 v[210:213], v145 offset:39936
	global_load_lds_dwordx4 v[220:221], off
	v_lshl_add_u64 v[220:221], s[42:43], 0, v[132:133]
	s_mov_b32 m0, s29
	s_nop 0
	global_load_lds_dwordx4 v[220:221], off
	s_waitcnt vmcnt(8)
	s_waitcnt lgkmcnt(0)
	s_barrier
	s_waitcnt lgkmcnt(0)
	v_mfma_f32_16x16x32_bf16 v[126:129], v[146:149], v[178:181], v[126:129]
	v_mfma_f32_16x16x32_bf16 v[122:125], v[154:157], v[178:181], v[122:125]
	v_mfma_f32_16x16x32_bf16 v[118:121], v[146:149], v[186:189], v[118:121]
	v_mfma_f32_16x16x32_bf16 v[110:113], v[154:157], v[186:189], v[110:113]
	v_mfma_f32_16x16x32_bf16 v[102:105], v[146:149], v[198:201], v[102:105]
	v_mfma_f32_16x16x32_bf16 v[94:97], v[154:157], v[198:201], v[94:97]
	v_mfma_f32_16x16x32_bf16 v[86:89], v[146:149], v[206:209], v[86:89]
	v_mfma_f32_16x16x32_bf16 v[78:81], v[154:157], v[206:209], v[78:81]
	v_mfma_f32_16x16x32_bf16 v[126:129], v[150:153], v[182:185], v[126:129]
	v_mfma_f32_16x16x32_bf16 v[122:125], v[158:161], v[182:185], v[122:125]
	v_mfma_f32_16x16x32_bf16 v[118:121], v[150:153], v[190:193], v[118:121]
	v_mfma_f32_16x16x32_bf16 v[110:113], v[158:161], v[190:193], v[110:113]
	v_mfma_f32_16x16x32_bf16 v[102:105], v[150:153], v[202:205], v[102:105]
	v_mfma_f32_16x16x32_bf16 v[94:97], v[158:161], v[202:205], v[94:97]
	v_mfma_f32_16x16x32_bf16 v[86:89], v[150:153], v[210:213], v[86:89]
	v_mfma_f32_16x16x32_bf16 v[78:81], v[158:161], v[210:213], v[78:81]
	v_mfma_f32_16x16x32_bf16 v[114:117], v[162:165], v[178:181], v[114:117]
	v_mfma_f32_16x16x32_bf16 v[106:109], v[170:173], v[178:181], v[106:109]
	v_mfma_f32_16x16x32_bf16 v[98:101], v[162:165], v[186:189], v[98:101]
	v_mfma_f32_16x16x32_bf16 v[90:93], v[170:173], v[186:189], v[90:93]
	v_mfma_f32_16x16x32_bf16 v[82:85], v[162:165], v[198:201], v[82:85]
	v_mfma_f32_16x16x32_bf16 v[74:77], v[170:173], v[198:201], v[74:77]
	v_mfma_f32_16x16x32_bf16 v[70:73], v[162:165], v[206:209], v[70:73]
	v_mfma_f32_16x16x32_bf16 v[66:69], v[170:173], v[206:209], v[66:69]
	v_mfma_f32_16x16x32_bf16 v[114:117], v[166:169], v[182:185], v[114:117]
	v_mfma_f32_16x16x32_bf16 v[106:109], v[174:177], v[182:185], v[106:109]
	v_mfma_f32_16x16x32_bf16 v[98:101], v[166:169], v[190:193], v[98:101]
	v_mfma_f32_16x16x32_bf16 v[90:93], v[174:177], v[190:193], v[90:93]
	v_mfma_f32_16x16x32_bf16 v[82:85], v[166:169], v[202:205], v[82:85]
	v_mfma_f32_16x16x32_bf16 v[74:77], v[174:177], v[202:205], v[74:77]
	v_mfma_f32_16x16x32_bf16 v[70:73], v[166:169], v[210:213], v[70:73]
	v_mfma_f32_16x16x32_bf16 v[66:69], v[174:177], v[210:213], v[66:69]
	s_barrier
; #define PG8_STAGE(bufoff, gbase, voff) do { _Pragma("unroll") for (int _i = 0; _i < 2; ++_i) \
;         __builtin_amdgcn_global_load_lds((const unsigned*)((const char*)(gbase) + (voff)[_i]), (PG8_LAS unsigned*)(lds + (bufoff) + ldsw + _i * 8192), 16, 0, 0); } while (0)
; #define PG8_LDA(dst, b, h) do { _Pragma("unroll") for (int m = 0; m < 4; ++m) _Pragma("unroll") for (int k = 0; k < 2; ++k) dst[m][k] = *(const PG8_LAS bf16x8*)(lds + PG8_SA(b, h) + aoff + m * 2048 + k * 1024); } while (0)
; #define PG8_LDB(dst, b, h) do { _Pragma("unroll") for (int n = 0; n < 2; ++n) _Pragma("unroll") for (int k = 0; k < 2; ++k) dst[n][k] = *(const PG8_LAS bf16x8*)(lds + PG8_SB(b, h) + boff + n * 2048 + k * 1024); } while (0)
; #define PG8_MMA(ai, bj, At, Bt) do { __builtin_amdgcn_s_setprio(1); _Pragma("unroll") for (int m = 0; m < 4; ++m) _Pragma("unroll") for (int n = 0; n < 2; ++n) _Pragma("unroll") for (int k = 0; k < 2; ++k) \
;         acc[ai][bj][m][n] = __builtin_amdgcn_mfma_f32_16x16x32_bf16(Bt[n][k], At[m][k], acc[ai][bj][m][n], 0, 0, 0); __builtin_amdgcn_s_setprio(0); } while (0)
; #define PG8_WAIT_V(n) asm volatile("s_waitcnt vmcnt(" #n ")" ::: "memory")
; #define PG8_WAIT_L(n) asm volatile("s_waitcnt lgkmcnt(" #n ")" ::: "memory")
; #define PG8_BAR __builtin_amdgcn_s_barrier()
; #define PG8_SCHED __builtin_amdgcn_sched_barrier(0)
; template <class Epi, class Sched, bool ALIGN_EPI = false, bool SP2 = false>
; __device__ __forceinline__ void gemm_phase(PG8_LAS unsigned char* lds, const Gemm g, const Sched& S, const Epi& E) {
;     ...
;             PG8_LDB(B0, 1, 0); PG8_LDB(B1, 1, 1); PG8_SCHED; PG8_LDA(At, 1, 0); PG8_STAGE(PG8_SA(0, 1), a2 + hstep, voffA);
;             PG8_WAIT_V(8); PG8_WAIT_L(0); PG8_BAR; PG8_MMA(0, 0, At, B0); PG8_MMA(0, 1, At, B1); PG8_BAR; PG8_SCHED;
;             PG8_LDA(At, 1, 1); PG8_STAGE(PG8_SB(1, 0), b3, voffB); PG8_STAGE(PG8_SB(1, 1), b3 + hstep, voffB); PG8_STAGE(PG8_SA(1, 0), a3, voffA);
;             PG8_WAIT_V(8); PG8_WAIT_L(0); PG8_BAR; PG8_MMA(1, 0, At, B0); PG8_MMA(1, 1, At, B1); PG8_BAR; PG8_SCHED;
	s_add_i32 s42, s55, s5
	v_lshl_add_u64 v[140:141], v[140:141], 0, s[58:59]
	s_mov_b32 m0, s42
	ds_read_b128 v[178:181], v145 offset:49152
	ds_read_b128 v[182:185], v145 offset:50176
	ds_read_b128 v[186:189], v145 offset:51200
	ds_read_b128 v[190:193], v145 offset:52224
	ds_read_b128 v[198:201], v145 offset:53248
	ds_read_b128 v[202:205], v145 offset:54272
	ds_read_b128 v[206:209], v145 offset:55296
	ds_read_b128 v[210:213], v145 offset:56320
	global_load_lds_dwordx4 v[140:141], off
	s_add_i32 m0, s42, 0x2000
	s_add_u32 s40, s40, 0x40080
	v_lshl_add_u64 v[140:141], v[214:215], 0, s[58:59]
	s_addc_u32 s41, s41, 0
	s_add_i32 s42, s63, s5
	global_load_lds_dwordx4 v[140:141], off
	v_lshl_add_u64 v[140:141], s[40:41], 0, v[0:1]
	s_mov_b32 m0, s42
	s_nop 0
	global_load_lds_dwordx4 v[140:141], off
	v_lshl_add_u64 v[140:141], s[40:41], 0, v[130:131]
	s_add_i32 m0, s42, 0x2000
	s_nop 0
	global_load_lds_dwordx4 v[140:141], off
	v_lshl_add_u64 v[140:141], v[216:217], 0, s[58:59]
	s_mov_b32 m0, s37
	s_nop 0
	global_load_lds_dwordx4 v[140:141], off
	v_lshl_add_u64 v[140:141], v[218:219], 0, s[58:59]
	s_mov_b32 m0, s44
	s_nop 0
	global_load_lds_dwordx4 v[140:141], off
	s_waitcnt vmcnt(8)
	s_waitcnt lgkmcnt(0)
	s_barrier
	s_waitcnt lgkmcnt(0)
	v_mfma_f32_16x16x32_bf16 v[62:65], v[146:149], v[178:181], v[62:65]
	v_mfma_f32_16x16x32_bf16 v[58:61], v[154:157], v[178:181], v[58:61]
	v_mfma_f32_16x16x32_bf16 v[54:57], v[146:149], v[186:189], v[54:57]
	v_mfma_f32_16x16x32_bf16 v[46:49], v[154:157], v[186:189], v[46:49]
	v_mfma_f32_16x16x32_bf16 v[38:41], v[146:149], v[198:201], v[38:41]
	v_mfma_f32_16x16x32_bf16 v[30:33], v[154:157], v[198:201], v[30:33]
	v_mfma_f32_16x16x32_bf16 v[22:25], v[146:149], v[206:209], v[22:25]
	v_mfma_f32_16x16x32_bf16 v[14:17], v[154:157], v[206:209], v[14:17]
	v_mfma_f32_16x16x32_bf16 v[62:65], v[150:153], v[182:185], v[62:65]
	v_mfma_f32_16x16x32_bf16 v[58:61], v[158:161], v[182:185], v[58:61]
	v_mfma_f32_16x16x32_bf16 v[54:57], v[150:153], v[190:193], v[54:57]
	v_mfma_f32_16x16x32_bf16 v[46:49], v[158:161], v[190:193], v[46:49]
	v_mfma_f32_16x16x32_bf16 v[38:41], v[150:153], v[202:205], v[38:41]
	v_mfma_f32_16x16x32_bf16 v[30:33], v[158:161], v[202:205], v[30:33]
	v_mfma_f32_16x16x32_bf16 v[22:25], v[150:153], v[210:213], v[22:25]
	v_mfma_f32_16x16x32_bf16 v[14:17], v[158:161], v[210:213], v[14:17]
	v_mfma_f32_16x16x32_bf16 v[50:53], v[162:165], v[178:181], v[50:53]
	v_mfma_f32_16x16x32_bf16 v[42:45], v[170:173], v[178:181], v[42:45]
	v_mfma_f32_16x16x32_bf16 v[34:37], v[162:165], v[186:189], v[34:37]
	v_mfma_f32_16x16x32_bf16 v[26:29], v[170:173], v[186:189], v[26:29]
	v_mfma_f32_16x16x32_bf16 v[18:21], v[162:165], v[198:201], v[18:21]
	v_mfma_f32_16x16x32_bf16 v[10:13], v[170:173], v[198:201], v[10:13]
	v_mfma_f32_16x16x32_bf16 v[6:9], v[162:165], v[206:209], v[6:9]
	v_mfma_f32_16x16x32_bf16 v[2:5], v[170:173], v[206:209], v[2:5]
	v_mfma_f32_16x16x32_bf16 v[50:53], v[166:169], v[182:185], v[50:53]
	v_mfma_f32_16x16x32_bf16 v[42:45], v[174:177], v[182:185], v[42:45]
	v_mfma_f32_16x16x32_bf16 v[34:37], v[166:169], v[190:193], v[34:37]
	v_mfma_f32_16x16x32_bf16 v[26:29], v[174:177], v[190:193], v[26:29]
	v_mfma_f32_16x16x32_bf16 v[18:21], v[166:169], v[202:205], v[18:21]
	v_mfma_f32_16x16x32_bf16 v[10:13], v[174:177], v[202:205], v[10:13]
	v_mfma_f32_16x16x32_bf16 v[6:9], v[166:169], v[210:213], v[6:9]
	v_mfma_f32_16x16x32_bf16 v[2:5], v[174:177], v[210:213], v[2:5]
	s_barrier
	s_add_i32 s54, s54, 2
	s_add_u32 s38, s38, 0x100
	s_addc_u32 s39, s39, 0
	s_add_u32 s50, s50, 0x100
	s_addc_u32 s51, s51, 0
	v_readfirstlane_b32 s98, v195
	s_cmp_lt_u32 s98, 0x100
	s_cbranch_scc0 .Lprio_skip_767
	s_setprio 1
.Lprio_skip_767:
	s_cmp_gt_u32 s54, 13
	s_cbranch_scc1 .Lpeel_done_767

; #define PG8_STAGE(bufoff, gbase, voff) do { _Pragma("unroll") for (int _i = 0; _i < 2; ++_i) \
;         __builtin_amdgcn_global_load_lds((const unsigned*)((const char*)(gbase) + (voff)[_i]), (PG8_LAS unsigned*)(lds + (bufoff) + ldsw + _i * 8192), 16, 0, 0); } while (0)
; #define PG8_LDA(dst, b, h) do { _Pragma("unroll") for (int m = 0; m < 4; ++m) _Pragma("unroll") for (int k = 0; k < 2; ++k) dst[m][k] = *(const PG8_LAS bf16x8*)(lds + PG8_SA(b, h) + aoff + m * 2048 + k * 1024); } while (0)
; #define PG8_LDB(dst, b, h) do { _Pragma("unroll") for (int n = 0; n < 2; ++n) _Pragma("unroll") for (int k = 0; k < 2; ++k) dst[n][k] = *(const PG8_LAS bf16x8*)(lds + PG8_SB(b, h) + boff + n * 2048 + k * 1024); } while (0)
; #define PG8_WAIT_V(n) asm volatile("s_waitcnt vmcnt(" #n ")" ::: "memory")
; #define PG8_WAIT_L(n) asm volatile("s_waitcnt lgkmcnt(" #n ")" ::: "memory")
; #define PG8_BAR __builtin_amdgcn_s_barrier()
; #define PG8_SCHED __builtin_amdgcn_sched_barrier(0)
; template <class Epi, class Sched, bool ALIGN_EPI = false, bool SP2 = false>
; __device__ __forceinline__ void gemm_phase(PG8_LAS unsigned char* lds, const Gemm g, const Sched& S, const Epi& E) {
;     ...
;         const char* nA = has_next ? (const char*)g.A + (size_t)nxt.pm * tstep : cA; const char* nB = has_next ? (const char*)g.Bt + (size_t)nxt.pn * tstep : cB;
;         for (int t = 0; t < nt; t += 2) {
;             const bool last = (t == nt - 2);
;             const char* a1 = cA + (size_t)(t + 1) * kstep;
;             const char* a2 = last ? nA : cA + (size_t)(t + 2) * kstep; const char* b2 = last ? nB : cB + (size_t)(t + 2) * kstep;
;             const char* a3 = a2 + kstep; const char* b3 = b2 + kstep;
;             if (last && has_next) S.a_ready(nxt);
;             if constexpr (SP2) {
;             PG8_LDB(B0, 0, 0); PG8_LDB(B1, 0, 1); PG8_SCHED; PG8_LDA(At, 0, 0); PG8_STAGE(PG8_SA(1, 1), a1 + hstep, voffA);
;             PG8_WAIT_V(8); PG8_WAIT_L(0); PG8_BAR; PG8_MMA(0, 0, At, B0); PG8_MMA(0, 1, At, B1); PG8_BAR; PG8_SCHED;
;             PG8_LDA(At, 0, 1); PG8_STAGE(PG8_SB(0, 0), b2, voffB); PG8_STAGE(PG8_SB(0, 1), b2 + hstep, voffB); PG8_STAGE(PG8_SA(0, 0), a2, voffA);
;             PG8_WAIT_V(8); PG8_WAIT_L(0); PG8_BAR; PG8_MMA(1, 0, At, B0); PG8_MMA(1, 1, At, B1); PG8_BAR; PG8_SCHED;
.LBB0_806:
	s_add_u32 s38, s38, 0x80
	s_addc_u32 s39, s39, 0
	s_add_u32 s86, s40, 0x100
	s_addc_u32 s87, s41, 0
	s_mov_b32 s40, 0
	s_waitcnt vmcnt(0)
	s_add_i32 vcc_lo, s40, 2
	s_add_u32 s72, s38, 0x80
	s_addc_u32 s41, s39, 0
	s_add_i32 vcc_hi, 0, 0x10000
	s_cmp_eq_u32 s65, s40
	s_cselect_b32 s41, s9, s41
	s_cselect_b32 s40, s8, s72
	v_add_u32_e32 v0, vcc_hi, v250
	s_cselect_b32 s73, s11, s87
	s_cselect_b32 s72, s10, s86
	s_add_i32 s78, 0, 0x14000
	ds_read_b128 v[130:133], v0
	ds_read_b128 v[134:137], v0 offset:1024
	ds_read_b128 v[138:141], v0 offset:2048
	ds_read_b128 v[142:145], v0 offset:3072
	v_add_u32_e32 v0, s78, v250
	ds_read_b128 v[146:149], v0
	ds_read_b128 v[150:153], v0 offset:1024
	ds_read_b128 v[154:157], v0 offset:2048
	ds_read_b128 v[158:161], v0 offset:3072
	v_lshl_add_u64 v[210:211], s[38:39], 0, v[206:207]
	s_add_i32 m0, s47, 0xc000
	ds_read_b128 v[162:165], v252
	ds_read_b128 v[166:169], v252 offset:1024
	ds_read_b128 v[170:173], v252 offset:2048
	ds_read_b128 v[174:177], v252 offset:3072
	ds_read_b128 v[178:181], v252 offset:4096
	ds_read_b128 v[182:185], v252 offset:5120
	ds_read_b128 v[186:189], v252 offset:6144
	ds_read_b128 v[190:193], v252 offset:7168
	global_load_lds_dwordx4 v[210:211], off
	v_lshl_add_u64 v[210:211], s[38:39], 0, v[208:209]
	s_add_i32 m0, s47, 0xe000
	s_nop 0
	global_load_lds_dwordx4 v[210:211], off
	s_waitcnt vmcnt(8)
	s_waitcnt lgkmcnt(0)
	s_barrier
	s_waitcnt lgkmcnt(0)
	v_mfma_f32_16x16x32_bf16 v[126:129], v[130:133], v[162:165], 0
	v_mfma_f32_16x16x32_bf16 v[122:125], v[138:141], v[162:165], 0
	v_mfma_f32_16x16x32_bf16 v[110:113], v[130:133], v[170:173], 0
	v_mfma_f32_16x16x32_bf16 v[106:109], v[138:141], v[170:173], 0
	v_mfma_f32_16x16x32_bf16 v[94:97], v[130:133], v[178:181], 0
	v_mfma_f32_16x16x32_bf16 v[90:93], v[138:141], v[178:181], 0
	v_mfma_f32_16x16x32_bf16 v[78:81], v[130:133], v[186:189], 0
	v_mfma_f32_16x16x32_bf16 v[74:77], v[138:141], v[186:189], 0
	v_mfma_f32_16x16x32_bf16 v[126:129], v[134:137], v[166:169], v[126:129]
	v_mfma_f32_16x16x32_bf16 v[122:125], v[142:145], v[166:169], v[122:125]
	v_mfma_f32_16x16x32_bf16 v[110:113], v[134:137], v[174:177], v[110:113]
	v_mfma_f32_16x16x32_bf16 v[106:109], v[142:145], v[174:177], v[106:109]
	v_mfma_f32_16x16x32_bf16 v[94:97], v[134:137], v[182:185], v[94:97]
	v_mfma_f32_16x16x32_bf16 v[90:93], v[142:145], v[182:185], v[90:93]
	v_mfma_f32_16x16x32_bf16 v[78:81], v[134:137], v[190:193], v[78:81]
	v_mfma_f32_16x16x32_bf16 v[74:77], v[142:145], v[190:193], v[74:77]
	v_mfma_f32_16x16x32_bf16 v[118:121], v[146:149], v[162:165], 0
	v_mfma_f32_16x16x32_bf16 v[114:117], v[154:157], v[162:165], 0
	v_mfma_f32_16x16x32_bf16 v[102:105], v[146:149], v[170:173], 0
	v_mfma_f32_16x16x32_bf16 v[98:101], v[154:157], v[170:173], 0
	v_mfma_f32_16x16x32_bf16 v[86:89], v[146:149], v[178:181], 0
	v_mfma_f32_16x16x32_bf16 v[82:85], v[154:157], v[178:181], 0
	v_mfma_f32_16x16x32_bf16 v[70:73], v[146:149], v[186:189], 0
	v_mfma_f32_16x16x32_bf16 v[66:69], v[154:157], v[186:189], 0
	v_mfma_f32_16x16x32_bf16 v[118:121], v[150:153], v[166:169], v[118:121]
	v_mfma_f32_16x16x32_bf16 v[114:117], v[158:161], v[166:169], v[114:117]
	v_mfma_f32_16x16x32_bf16 v[102:105], v[150:153], v[174:177], v[102:105]
	v_mfma_f32_16x16x32_bf16 v[98:101], v[158:161], v[174:177], v[98:101]
	v_mfma_f32_16x16x32_bf16 v[86:89], v[150:153], v[182:185], v[86:89]
	v_mfma_f32_16x16x32_bf16 v[82:85], v[158:161], v[182:185], v[82:85]
	v_mfma_f32_16x16x32_bf16 v[70:73], v[150:153], v[190:193], v[70:73]
	v_mfma_f32_16x16x32_bf16 v[66:69], v[158:161], v[190:193], v[66:69]
	s_barrier
	s_add_i32 s79, vcc_hi, s44
	v_lshl_add_u64 v[210:211], s[72:73], 0, v[198:199]
	s_mov_b32 m0, s79
	ds_read_b128 v[162:165], v252 offset:16384
	ds_read_b128 v[166:169], v252 offset:17408
	ds_read_b128 v[170:173], v252 offset:18432
	ds_read_b128 v[174:177], v252 offset:19456
	ds_read_b128 v[178:181], v252 offset:20480
	ds_read_b128 v[182:185], v252 offset:21504
	ds_read_b128 v[186:189], v252 offset:22528
	ds_read_b128 v[190:193], v252 offset:23552
	global_load_lds_dwordx4 v[210:211], off
	s_add_i32 m0, s79, 0x2000
	v_lshl_add_u64 v[212:213], s[72:73], 0, v[200:201]
	s_add_u32 s72, s72, s30
	s_addc_u32 s73, s73, 0
	s_add_i32 s78, s78, s44
	global_load_lds_dwordx4 v[212:213], off
	v_lshl_add_u64 v[214:215], s[72:73], 0, v[198:199]
	s_mov_b32 m0, s78
	v_lshl_add_u64 v[216:217], s[72:73], 0, v[200:201]
	global_load_lds_dwordx4 v[214:215], off
	s_add_i32 m0, s78, 0x2000
	v_lshl_add_u64 v[218:219], s[40:41], 0, v[198:199]
	global_load_lds_dwordx4 v[216:217], off
	s_mov_b32 m0, s47
	v_lshl_add_u64 v[220:221], s[40:41], 0, v[200:201]
	global_load_lds_dwordx4 v[218:219], off
	s_mov_b32 m0, s48
	s_nop 0
	global_load_lds_dwordx4 v[220:221], off
	s_waitcnt vmcnt(8)
	s_waitcnt lgkmcnt(0)
	s_barrier
; #define PG8_STAGE(bufoff, gbase, voff) do { _Pragma("unroll") for (int _i = 0; _i < 2; ++_i) \
;         __builtin_amdgcn_global_load_lds((const unsigned*)((const char*)(gbase) + (voff)[_i]), (PG8_LAS unsigned*)(lds + (bufoff) + ldsw + _i * 8192), 16, 0, 0); } while (0)
; #define PG8_LDA(dst, b, h) do { _Pragma("unroll") for (int m = 0; m < 4; ++m) _Pragma("unroll") for (int k = 0; k < 2; ++k) dst[m][k] = *(const PG8_LAS bf16x8*)(lds + PG8_SA(b, h) + aoff + m * 2048 + k * 1024); } while (0)
; #define PG8_LDB(dst, b, h) do { _Pragma("unroll") for (int n = 0; n < 2; ++n) _Pragma("unroll") for (int k = 0; k < 2; ++k) dst[n][k] = *(const PG8_LAS bf16x8*)(lds + PG8_SB(b, h) + boff + n * 2048 + k * 1024); } while (0)
; #define PG8_MMA(ai, bj, At, Bt) do { __builtin_amdgcn_s_setprio(1); _Pragma("unroll") for (int m = 0; m < 4; ++m) _Pragma("unroll") for (int n = 0; n < 2; ++n) _Pragma("unroll") for (int k = 0; k < 2; ++k) \
;         acc[ai][bj][m][n] = __builtin_amdgcn_mfma_f32_16x16x32_bf16(Bt[n][k], At[m][k], acc[ai][bj][m][n], 0, 0, 0); __builtin_amdgcn_s_setprio(0); } while (0)
; #define PG8_WAIT_V(n) asm volatile("s_waitcnt vmcnt(" #n ")" ::: "memory")
; #define PG8_WAIT_L(n) asm volatile("s_waitcnt lgkmcnt(" #n ")" ::: "memory")
; #define PG8_BAR __builtin_amdgcn_s_barrier()
; #define PG8_SCHED __builtin_amdgcn_sched_barrier(0)
; template <class Epi, class Sched, bool ALIGN_EPI = false, bool SP2 = false>
; __device__ __forceinline__ void gemm_phase(PG8_LAS unsigned char* lds, const Gemm g, const Sched& S, const Epi& E) {
;     ...
;             PG8_WAIT_V(8); PG8_WAIT_L(0); PG8_BAR; PG8_MMA(1, 0, At, B0); PG8_MMA(1, 1, At, B1); PG8_BAR; PG8_SCHED;
;             PG8_LDB(B0, 1, 0); PG8_LDB(B1, 1, 1); PG8_SCHED; PG8_LDA(At, 1, 0); PG8_STAGE(PG8_SA(0, 1), a2 + hstep, voffA);
;             PG8_WAIT_V(8); PG8_WAIT_L(0); PG8_BAR; PG8_MMA(0, 0, At, B0); PG8_MMA(0, 1, At, B1); PG8_BAR; PG8_SCHED;
;             PG8_LDA(At, 1, 1); PG8_STAGE(PG8_SB(1, 0), b3, voffB); PG8_STAGE(PG8_SB(1, 1), b3 + hstep, voffB); PG8_STAGE(PG8_SA(1, 0), a3, voffA);
;             PG8_WAIT_V(8); PG8_WAIT_L(0); PG8_BAR; PG8_MMA(1, 0, At, B0); PG8_MMA(1, 1, At, B1); PG8_BAR; PG8_SCHED;
	s_waitcnt lgkmcnt(0)
	v_mfma_f32_16x16x32_bf16 v[62:65], v[130:133], v[162:165], 0
	v_mfma_f32_16x16x32_bf16 v[58:61], v[138:141], v[162:165], 0
	v_mfma_f32_16x16x32_bf16 v[50:53], v[130:133], v[170:173], 0
	v_mfma_f32_16x16x32_bf16 v[42:45], v[138:141], v[170:173], 0
	v_mfma_f32_16x16x32_bf16 v[34:37], v[130:133], v[178:181], 0
	v_mfma_f32_16x16x32_bf16 v[26:29], v[138:141], v[178:181], 0
	v_mfma_f32_16x16x32_bf16 v[18:21], v[130:133], v[186:189], 0
	v_mfma_f32_16x16x32_bf16 v[14:17], v[138:141], v[186:189], 0
	v_mfma_f32_16x16x32_bf16 v[62:65], v[134:137], v[166:169], v[62:65]
	v_mfma_f32_16x16x32_bf16 v[58:61], v[142:145], v[166:169], v[58:61]
	v_mfma_f32_16x16x32_bf16 v[50:53], v[134:137], v[174:177], v[50:53]
	v_mfma_f32_16x16x32_bf16 v[42:45], v[142:145], v[174:177], v[42:45]
	v_mfma_f32_16x16x32_bf16 v[34:37], v[134:137], v[182:185], v[34:37]
	v_mfma_f32_16x16x32_bf16 v[26:29], v[142:145], v[182:185], v[26:29]
	v_mfma_f32_16x16x32_bf16 v[18:21], v[134:137], v[190:193], v[18:21]
	v_mfma_f32_16x16x32_bf16 v[14:17], v[142:145], v[190:193], v[14:17]
	v_mfma_f32_16x16x32_bf16 v[54:57], v[146:149], v[162:165], 0
	v_mfma_f32_16x16x32_bf16 v[46:49], v[154:157], v[162:165], 0
	v_mfma_f32_16x16x32_bf16 v[38:41], v[146:149], v[170:173], 0
	v_mfma_f32_16x16x32_bf16 v[30:33], v[154:157], v[170:173], 0
	v_mfma_f32_16x16x32_bf16 v[22:25], v[146:149], v[178:181], 0
	v_mfma_f32_16x16x32_bf16 v[10:13], v[154:157], v[178:181], 0
	v_mfma_f32_16x16x32_bf16 v[6:9], v[146:149], v[186:189], 0
	v_mfma_f32_16x16x32_bf16 v[2:5], v[154:157], v[186:189], 0
	v_mfma_f32_16x16x32_bf16 v[54:57], v[150:153], v[166:169], v[54:57]
	v_mfma_f32_16x16x32_bf16 v[46:49], v[158:161], v[166:169], v[46:49]
	v_mfma_f32_16x16x32_bf16 v[38:41], v[150:153], v[174:177], v[38:41]
	v_mfma_f32_16x16x32_bf16 v[30:33], v[158:161], v[174:177], v[30:33]
	v_mfma_f32_16x16x32_bf16 v[22:25], v[150:153], v[182:185], v[22:25]
	v_mfma_f32_16x16x32_bf16 v[10:13], v[158:161], v[182:185], v[10:13]
	v_mfma_f32_16x16x32_bf16 v[6:9], v[150:153], v[190:193], v[6:9]
	v_mfma_f32_16x16x32_bf16 v[2:5], v[158:161], v[190:193], v[2:5]
	s_barrier
	s_add_i32 s72, 0, 0x18000
	v_add_u32_e32 v0, s72, v250
	s_add_i32 s73, 0, 0x1c000
	ds_read_b128 v[130:133], v0
	ds_read_b128 v[134:137], v0 offset:1024
	ds_read_b128 v[138:141], v0 offset:2048
	ds_read_b128 v[142:145], v0 offset:3072
	v_add_u32_e32 v0, s73, v250
	ds_read_b128 v[146:149], v0
	ds_read_b128 v[150:153], v0 offset:1024
	ds_read_b128 v[154:157], v0 offset:2048
	ds_read_b128 v[158:161], v0 offset:3072
	s_add_u32 s40, s40, s30
	s_addc_u32 s41, s41, 0
	s_mov_b32 m0, s49
	v_lshl_add_u64 v[222:223], s[40:41], 0, v[198:199]
	ds_read_b128 v[162:165], v252 offset:32768
	ds_read_b128 v[166:169], v252 offset:33792
	ds_read_b128 v[170:173], v252 offset:34816
	ds_read_b128 v[174:177], v252 offset:35840
	ds_read_b128 v[178:181], v252 offset:36864
	ds_read_b128 v[182:185], v252 offset:37888
	ds_read_b128 v[186:189], v252 offset:38912
	ds_read_b128 v[190:193], v252 offset:39936
	global_load_lds_dwordx4 v[222:223], off
	v_lshl_add_u64 v[222:223], s[40:41], 0, v[200:201]
	s_mov_b32 m0, s50
	s_nop 0
	global_load_lds_dwordx4 v[222:223], off
	s_waitcnt vmcnt(8)
	s_waitcnt lgkmcnt(0)
	s_barrier
	s_waitcnt lgkmcnt(0)
	v_mfma_f32_16x16x32_bf16 v[126:129], v[130:133], v[162:165], v[126:129]
	v_mfma_f32_16x16x32_bf16 v[122:125], v[138:141], v[162:165], v[122:125]
	v_mfma_f32_16x16x32_bf16 v[110:113], v[130:133], v[170:173], v[110:113]
	v_mfma_f32_16x16x32_bf16 v[106:109], v[138:141], v[170:173], v[106:109]
	v_mfma_f32_16x16x32_bf16 v[94:97], v[130:133], v[178:181], v[94:97]
	v_mfma_f32_16x16x32_bf16 v[90:93], v[138:141], v[178:181], v[90:93]
	v_mfma_f32_16x16x32_bf16 v[78:81], v[130:133], v[186:189], v[78:81]
	v_mfma_f32_16x16x32_bf16 v[74:77], v[138:141], v[186:189], v[74:77]
	v_mfma_f32_16x16x32_bf16 v[126:129], v[134:137], v[166:169], v[126:129]
	v_mfma_f32_16x16x32_bf16 v[122:125], v[142:145], v[166:169], v[122:125]
	v_mfma_f32_16x16x32_bf16 v[110:113], v[134:137], v[174:177], v[110:113]
	v_mfma_f32_16x16x32_bf16 v[106:109], v[142:145], v[174:177], v[106:109]
	v_mfma_f32_16x16x32_bf16 v[94:97], v[134:137], v[182:185], v[94:97]
	v_mfma_f32_16x16x32_bf16 v[90:93], v[142:145], v[182:185], v[90:93]
	v_mfma_f32_16x16x32_bf16 v[78:81], v[134:137], v[190:193], v[78:81]
	v_mfma_f32_16x16x32_bf16 v[74:77], v[142:145], v[190:193], v[74:77]
	v_mfma_f32_16x16x32_bf16 v[118:121], v[146:149], v[162:165], v[118:121]
	v_mfma_f32_16x16x32_bf16 v[114:117], v[154:157], v[162:165], v[114:117]
	v_mfma_f32_16x16x32_bf16 v[102:105], v[146:149], v[170:173], v[102:105]
	v_mfma_f32_16x16x32_bf16 v[98:101], v[154:157], v[170:173], v[98:101]
	v_mfma_f32_16x16x32_bf16 v[86:89], v[146:149], v[178:181], v[86:89]
	v_mfma_f32_16x16x32_bf16 v[82:85], v[154:157], v[178:181], v[82:85]
	v_mfma_f32_16x16x32_bf16 v[70:73], v[146:149], v[186:189], v[70:73]
	v_mfma_f32_16x16x32_bf16 v[66:69], v[154:157], v[186:189], v[66:69]
	v_mfma_f32_16x16x32_bf16 v[118:121], v[150:153], v[166:169], v[118:121]
	v_mfma_f32_16x16x32_bf16 v[114:117], v[158:161], v[166:169], v[114:117]
	v_mfma_f32_16x16x32_bf16 v[102:105], v[150:153], v[174:177], v[102:105]
	v_mfma_f32_16x16x32_bf16 v[98:101], v[158:161], v[174:177], v[98:101]
	v_mfma_f32_16x16x32_bf16 v[86:89], v[150:153], v[182:185], v[86:89]
	v_mfma_f32_16x16x32_bf16 v[82:85], v[158:161], v[182:185], v[82:85]
	v_mfma_f32_16x16x32_bf16 v[70:73], v[150:153], v[190:193], v[70:73]
	v_mfma_f32_16x16x32_bf16 v[66:69], v[158:161], v[190:193], v[66:69]
	s_barrier
; #define PG8_STAGE(bufoff, gbase, voff) do { _Pragma("unroll") for (int _i = 0; _i < 2; ++_i) \
;         __builtin_amdgcn_global_load_lds((const unsigned*)((const char*)(gbase) + (voff)[_i]), (PG8_LAS unsigned*)(lds + (bufoff) + ldsw + _i * 8192), 16, 0, 0); } while (0)
; #define PG8_LDA(dst, b, h) do { _Pragma("unroll") for (int m = 0; m < 4; ++m) _Pragma("unroll") for (int k = 0; k < 2; ++k) dst[m][k] = *(const PG8_LAS bf16x8*)(lds + PG8_SA(b, h) + aoff + m * 2048 + k * 1024); } while (0)
; #define PG8_LDB(dst, b, h) do { _Pragma("unroll") for (int n = 0; n < 2; ++n) _Pragma("unroll") for (int k = 0; k < 2; ++k) dst[n][k] = *(const PG8_LAS bf16x8*)(lds + PG8_SB(b, h) + boff + n * 2048 + k * 1024); } while (0)
; #define PG8_MMA(ai, bj, At, Bt) do { __builtin_amdgcn_s_setprio(1); _Pragma("unroll") for (int m = 0; m < 4; ++m) _Pragma("unroll") for (int n = 0; n < 2; ++n) _Pragma("unroll") for (int k = 0; k < 2; ++k) \
;         acc[ai][bj][m][n] = __builtin_amdgcn_mfma_f32_16x16x32_bf16(Bt[n][k], At[m][k], acc[ai][bj][m][n], 0, 0, 0); __builtin_amdgcn_s_setprio(0); } while (0)
; #define PG8_WAIT_V(n) asm volatile("s_waitcnt vmcnt(" #n ")" ::: "memory")
; #define PG8_WAIT_L(n) asm volatile("s_waitcnt lgkmcnt(" #n ")" ::: "memory")
; #define PG8_BAR __builtin_amdgcn_s_barrier()
; #define PG8_SCHED __builtin_amdgcn_sched_barrier(0)
; template <class Epi, class Sched, bool ALIGN_EPI = false, bool SP2 = false>
; __device__ __forceinline__ void gemm_phase(PG8_LAS unsigned char* lds, const Gemm g, const Sched& S, const Epi& E) {
;     ...
;             PG8_LDB(B0, 1, 0); PG8_LDB(B1, 1, 1); PG8_SCHED; PG8_LDA(At, 1, 0); PG8_STAGE(PG8_SA(0, 1), a2 + hstep, voffA);
;             PG8_WAIT_V(8); PG8_WAIT_L(0); PG8_BAR; PG8_MMA(0, 0, At, B0); PG8_MMA(0, 1, At, B1); PG8_BAR; PG8_SCHED;
;             PG8_LDA(At, 1, 1); PG8_STAGE(PG8_SB(1, 0), b3, voffB); PG8_STAGE(PG8_SB(1, 1), b3 + hstep, voffB); PG8_STAGE(PG8_SA(1, 0), a3, voffA);
;             PG8_WAIT_V(8); PG8_WAIT_L(0); PG8_BAR; PG8_MMA(1, 0, At, B0); PG8_MMA(1, 1, At, B1); PG8_BAR; PG8_SCHED;
	s_add_i32 s40, s72, s44
	v_lshl_add_u64 v[210:211], v[210:211], 0, s[58:59]
	s_mov_b32 m0, s40
	ds_read_b128 v[162:165], v252 offset:49152
	ds_read_b128 v[166:169], v252 offset:50176
	ds_read_b128 v[170:173], v252 offset:51200
	ds_read_b128 v[174:177], v252 offset:52224
	ds_read_b128 v[178:181], v252 offset:53248
	ds_read_b128 v[182:185], v252 offset:54272
	ds_read_b128 v[186:189], v252 offset:55296
	ds_read_b128 v[190:193], v252 offset:56320
	global_load_lds_dwordx4 v[210:211], off
	v_lshl_add_u64 v[210:211], v[212:213], 0, s[58:59]
	s_add_i32 m0, s40, 0x2000
	s_add_i32 s40, s73, s44
	global_load_lds_dwordx4 v[210:211], off
	v_lshl_add_u64 v[210:211], v[214:215], 0, s[58:59]
	s_mov_b32 m0, s40
	s_nop 0
	global_load_lds_dwordx4 v[210:211], off
	v_lshl_add_u64 v[210:211], v[216:217], 0, s[58:59]
	s_add_i32 m0, s40, 0x2000
	s_nop 0
	global_load_lds_dwordx4 v[210:211], off
	v_lshl_add_u64 v[210:211], v[218:219], 0, s[58:59]
	s_mov_b32 m0, s55
	s_nop 0
	global_load_lds_dwordx4 v[210:211], off
	v_lshl_add_u64 v[210:211], v[220:221], 0, s[58:59]
	s_mov_b32 m0, s63
	s_nop 0
	global_load_lds_dwordx4 v[210:211], off
	s_waitcnt vmcnt(8)
	s_waitcnt lgkmcnt(0)
	s_barrier
	s_waitcnt lgkmcnt(0)
	v_mfma_f32_16x16x32_bf16 v[62:65], v[130:133], v[162:165], v[62:65]
	v_mfma_f32_16x16x32_bf16 v[58:61], v[138:141], v[162:165], v[58:61]
	v_mfma_f32_16x16x32_bf16 v[50:53], v[130:133], v[170:173], v[50:53]
	v_mfma_f32_16x16x32_bf16 v[42:45], v[138:141], v[170:173], v[42:45]
	v_mfma_f32_16x16x32_bf16 v[34:37], v[130:133], v[178:181], v[34:37]
	v_mfma_f32_16x16x32_bf16 v[26:29], v[138:141], v[178:181], v[26:29]
	v_mfma_f32_16x16x32_bf16 v[18:21], v[130:133], v[186:189], v[18:21]
	v_mfma_f32_16x16x32_bf16 v[14:17], v[138:141], v[186:189], v[14:17]
	v_mfma_f32_16x16x32_bf16 v[62:65], v[134:137], v[166:169], v[62:65]
	v_mfma_f32_16x16x32_bf16 v[58:61], v[142:145], v[166:169], v[58:61]
	v_mfma_f32_16x16x32_bf16 v[50:53], v[134:137], v[174:177], v[50:53]
	v_mfma_f32_16x16x32_bf16 v[42:45], v[142:145], v[174:177], v[42:45]
	v_mfma_f32_16x16x32_bf16 v[34:37], v[134:137], v[182:185], v[34:37]
	v_mfma_f32_16x16x32_bf16 v[26:29], v[142:145], v[182:185], v[26:29]
	v_mfma_f32_16x16x32_bf16 v[18:21], v[134:137], v[190:193], v[18:21]
	v_mfma_f32_16x16x32_bf16 v[14:17], v[142:145], v[190:193], v[14:17]
	v_mfma_f32_16x16x32_bf16 v[54:57], v[146:149], v[162:165], v[54:57]
	v_mfma_f32_16x16x32_bf16 v[46:49], v[154:157], v[162:165], v[46:49]
	v_mfma_f32_16x16x32_bf16 v[38:41], v[146:149], v[170:173], v[38:41]
	v_mfma_f32_16x16x32_bf16 v[30:33], v[154:157], v[170:173], v[30:33]
	v_mfma_f32_16x16x32_bf16 v[22:25], v[146:149], v[178:181], v[22:25]
	v_mfma_f32_16x16x32_bf16 v[10:13], v[154:157], v[178:181], v[10:13]
	v_mfma_f32_16x16x32_bf16 v[6:9], v[146:149], v[186:189], v[6:9]
	v_mfma_f32_16x16x32_bf16 v[2:5], v[154:157], v[186:189], v[2:5]
	v_mfma_f32_16x16x32_bf16 v[54:57], v[150:153], v[166:169], v[54:57]
	v_mfma_f32_16x16x32_bf16 v[46:49], v[158:161], v[166:169], v[46:49]
	v_mfma_f32_16x16x32_bf16 v[38:41], v[150:153], v[174:177], v[38:41]
	v_mfma_f32_16x16x32_bf16 v[30:33], v[158:161], v[174:177], v[30:33]
	v_mfma_f32_16x16x32_bf16 v[22:25], v[150:153], v[182:185], v[22:25]
	v_mfma_f32_16x16x32_bf16 v[10:13], v[158:161], v[182:185], v[10:13]
	v_mfma_f32_16x16x32_bf16 v[6:9], v[150:153], v[190:193], v[6:9]
	v_mfma_f32_16x16x32_bf16 v[2:5], v[158:161], v[190:193], v[2:5]
	s_barrier
	s_add_u32 s38, s38, 0x100
	s_addc_u32 s39, s39, 0
	s_add_u32 s86, s86, 0x100
	s_addc_u32 s87, s87, 0
	v_readfirstlane_b32 s98, v195
	s_cmp_lt_u32 s98, 0x100
	s_cbranch_scc0 .Lprio_skip_807
	s_setprio 1
.Lprio_skip_807:
	s_cmp_ge_u32 vcc_lo, s93
	s_mov_b32 s40, vcc_lo
	s_cbranch_scc1 .Lpeel_done_807

; #define PG8_STAGE(bufoff, gbase, voff) do { _Pragma("unroll") for (int _i = 0; _i < 2; ++_i) \
;         __builtin_amdgcn_global_load_lds((const unsigned*)((const char*)(gbase) + (voff)[_i]), (PG8_LAS unsigned*)(lds + (bufoff) + ldsw + _i * 8192), 16, 0, 0); } while (0)
; #define PG8_LDA(dst, b, h) do { _Pragma("unroll") for (int m = 0; m < 4; ++m) _Pragma("unroll") for (int k = 0; k < 2; ++k) dst[m][k] = *(const PG8_LAS bf16x8*)(lds + PG8_SA(b, h) + aoff + m * 2048 + k * 1024); } while (0)
; #define PG8_LDB(dst, b, h) do { _Pragma("unroll") for (int n = 0; n < 2; ++n) _Pragma("unroll") for (int k = 0; k < 2; ++k) dst[n][k] = *(const PG8_LAS bf16x8*)(lds + PG8_SB(b, h) + boff + n * 2048 + k * 1024); } while (0)
; #define PG8_MMA(ai, bj, At, Bt) do { __builtin_amdgcn_s_setprio(1); _Pragma("unroll") for (int m = 0; m < 4; ++m) _Pragma("unroll") for (int n = 0; n < 2; ++n) _Pragma("unroll") for (int k = 0; k < 2; ++k) \
;         acc[ai][bj][m][n] = __builtin_amdgcn_mfma_f32_16x16x32_bf16(Bt[n][k], At[m][k], acc[ai][bj][m][n], 0, 0, 0); __builtin_amdgcn_s_setprio(0); } while (0)
; #define PG8_WAIT_V(n) asm volatile("s_waitcnt vmcnt(" #n ")" ::: "memory")
; #define PG8_BAR __builtin_amdgcn_s_barrier()
; template <class Epi, class Sched, bool ALIGN_EPI = false, bool SP2 = false>
; __device__ __forceinline__ void gemm_phase(PG8_LAS unsigned char* lds, const Gemm g, const Sched& S, const Epi& E) {
;     ...
;         for (int t = 0; t < nt; t += 2) {
;             const bool last = (t == nt - 2);
;             const char* a1 = cA + (size_t)(t + 1) * kstep;
;             const char* a2 = last ? nA : cA + (size_t)(t + 2) * kstep; const char* b2 = last ? nB : cB + (size_t)(t + 2) * kstep;
;             const char* a3 = a2 + kstep; const char* b3 = b2 + kstep;
;             if (last && has_next) S.a_ready(nxt);
;             if constexpr (SP2) {
;             PG8_LDB(B0, 0, 0); PG8_LDB(B1, 0, 1); PG8_SCHED; PG8_LDA(At, 0, 0); PG8_STAGE(PG8_SA(1, 1), a1 + hstep, voffA);
;             PG8_WAIT_V(8); PG8_WAIT_L(0); PG8_BAR; PG8_MMA(0, 0, At, B0); PG8_MMA(0, 1, At, B1); PG8_BAR; PG8_SCHED;
;             PG8_LDA(At, 0, 1); PG8_STAGE(PG8_SB(0, 0), b2, voffB); PG8_STAGE(PG8_SB(0, 1), b2 + hstep, voffB); PG8_STAGE(PG8_SA(0, 0), a2, voffA);
;             PG8_WAIT_V(8); PG8_WAIT_L(0); PG8_BAR; PG8_MMA(1, 0, At, B0); PG8_MMA(1, 1, At, B1); PG8_BAR; PG8_SCHED;
.LBB0_832:
	s_add_u32 s30, s30, 0x80
	s_addc_u32 s31, s31, 0
	s_add_u32 s65, s38, 0x100
	s_addc_u32 s86, s39, 0
	s_mov_b32 s38, 0
	s_add_i32 s87, s38, 2
	s_add_u32 s72, s30, 0x80
	s_addc_u32 s39, s31, 0
	s_add_i32 s78, 0, 0x10000
	s_cmp_eq_u32 s54, s38
	s_cselect_b32 s39, s21, s39
	s_cselect_b32 s38, s20, s72
	v_add_u32_e32 v0, s78, v139
	s_cselect_b32 s73, s7, s86
	s_cselect_b32 s72, s6, s65
	s_add_i32 s79, 0, 0x14000
	ds_read_b128 v[142:145], v0
	ds_read_b128 v[146:149], v0 offset:1024
	ds_read_b128 v[150:153], v0 offset:2048
	ds_read_b128 v[154:157], v0 offset:3072
	v_add_u32_e32 v0, s79, v139
	ds_read_b128 v[158:161], v0
	ds_read_b128 v[162:165], v0 offset:1024
	ds_read_b128 v[166:169], v0 offset:2048
	ds_read_b128 v[170:173], v0 offset:3072
	v_lshl_add_u64 v[210:211], s[30:31], 0, v[134:135]
	s_add_i32 m0, s42, 0xc000
	ds_read_b128 v[174:177], v141
	ds_read_b128 v[178:181], v141 offset:1024
	ds_read_b128 v[182:185], v141 offset:2048
	ds_read_b128 v[186:189], v141 offset:3072
	ds_read_b128 v[190:193], v141 offset:4096
	ds_read_b128 v[198:201], v141 offset:5120
	ds_read_b128 v[202:205], v141 offset:6144
	ds_read_b128 v[206:209], v141 offset:7168
	global_load_lds_dwordx4 v[210:211], off
	v_lshl_add_u64 v[210:211], s[30:31], 0, v[136:137]
	s_add_i32 m0, s42, 0xe000
	s_nop 0
	global_load_lds_dwordx4 v[210:211], off
	s_waitcnt vmcnt(8)
	s_waitcnt lgkmcnt(0)
	s_barrier
	s_waitcnt lgkmcnt(0)
	v_mfma_f32_16x16x32_bf16 v[126:129], v[142:145], v[174:177], 0
	v_mfma_f32_16x16x32_bf16 v[122:125], v[150:153], v[174:177], 0
	v_mfma_f32_16x16x32_bf16 v[118:121], v[142:145], v[182:185], 0
	v_mfma_f32_16x16x32_bf16 v[114:117], v[150:153], v[182:185], 0
	v_mfma_f32_16x16x32_bf16 v[110:113], v[142:145], v[190:193], 0
	v_mfma_f32_16x16x32_bf16 v[102:105], v[150:153], v[190:193], 0
	v_mfma_f32_16x16x32_bf16 v[90:93], v[142:145], v[202:205], 0
	v_mfma_f32_16x16x32_bf16 v[82:85], v[150:153], v[202:205], 0
	v_mfma_f32_16x16x32_bf16 v[126:129], v[146:149], v[178:181], v[126:129]
	v_mfma_f32_16x16x32_bf16 v[122:125], v[154:157], v[178:181], v[122:125]
	v_mfma_f32_16x16x32_bf16 v[118:121], v[146:149], v[186:189], v[118:121]
	v_mfma_f32_16x16x32_bf16 v[114:117], v[154:157], v[186:189], v[114:117]
	v_mfma_f32_16x16x32_bf16 v[110:113], v[146:149], v[198:201], v[110:113]
	v_mfma_f32_16x16x32_bf16 v[102:105], v[154:157], v[198:201], v[102:105]
	v_mfma_f32_16x16x32_bf16 v[90:93], v[146:149], v[206:209], v[90:93]
	v_mfma_f32_16x16x32_bf16 v[82:85], v[154:157], v[206:209], v[82:85]
	v_mfma_f32_16x16x32_bf16 v[106:109], v[158:161], v[174:177], 0
	v_mfma_f32_16x16x32_bf16 v[98:101], v[166:169], v[174:177], 0
	v_mfma_f32_16x16x32_bf16 v[94:97], v[158:161], v[182:185], 0
	v_mfma_f32_16x16x32_bf16 v[86:89], v[166:169], v[182:185], 0
	v_mfma_f32_16x16x32_bf16 v[78:81], v[158:161], v[190:193], 0
	v_mfma_f32_16x16x32_bf16 v[74:77], v[166:169], v[190:193], 0
	v_mfma_f32_16x16x32_bf16 v[70:73], v[158:161], v[202:205], 0
	v_mfma_f32_16x16x32_bf16 v[66:69], v[166:169], v[202:205], 0
	v_mfma_f32_16x16x32_bf16 v[106:109], v[162:165], v[178:181], v[106:109]
	v_mfma_f32_16x16x32_bf16 v[98:101], v[170:173], v[178:181], v[98:101]
	v_mfma_f32_16x16x32_bf16 v[94:97], v[162:165], v[186:189], v[94:97]
	v_mfma_f32_16x16x32_bf16 v[86:89], v[170:173], v[186:189], v[86:89]
	v_mfma_f32_16x16x32_bf16 v[78:81], v[162:165], v[198:201], v[78:81]
	v_mfma_f32_16x16x32_bf16 v[74:77], v[170:173], v[198:201], v[74:77]
	v_mfma_f32_16x16x32_bf16 v[70:73], v[162:165], v[206:209], v[70:73]
	v_mfma_f32_16x16x32_bf16 v[66:69], v[170:173], v[206:209], v[66:69]
	s_barrier
	s_add_i32 s78, s78, s41
	v_lshl_add_u64 v[210:211], s[72:73], 0, v[132:133]
	s_mov_b32 m0, s78
	ds_read_b128 v[174:177], v141 offset:16384
	ds_read_b128 v[178:181], v141 offset:17408
	ds_read_b128 v[182:185], v141 offset:18432
	ds_read_b128 v[186:189], v141 offset:19456
	ds_read_b128 v[190:193], v141 offset:20480
	ds_read_b128 v[198:201], v141 offset:21504
	ds_read_b128 v[202:205], v141 offset:22528
	ds_read_b128 v[206:209], v141 offset:23552
	global_load_lds_dwordx4 v[210:211], off
	s_add_i32 m0, s78, 0x2000
	v_lshl_add_u64 v[212:213], s[72:73], 0, v[130:131]
	s_add_u32 s72, s72, s8
	s_addc_u32 s73, s73, 0
	s_add_i32 s78, s79, s41
	global_load_lds_dwordx4 v[212:213], off
	v_lshl_add_u64 v[214:215], s[72:73], 0, v[132:133]
	s_mov_b32 m0, s78
	v_lshl_add_u64 v[216:217], s[72:73], 0, v[130:131]
	global_load_lds_dwordx4 v[214:215], off
	s_add_i32 m0, s78, 0x2000
	v_lshl_add_u64 v[218:219], s[38:39], 0, v[132:133]
	global_load_lds_dwordx4 v[216:217], off
	s_mov_b32 m0, s42
	v_lshl_add_u64 v[220:221], s[38:39], 0, v[130:131]
	global_load_lds_dwordx4 v[218:219], off
	s_mov_b32 m0, s43
	s_nop 0
	global_load_lds_dwordx4 v[220:221], off
	s_waitcnt vmcnt(8)
	s_waitcnt lgkmcnt(0)
	s_barrier
; #define PG8_STAGE(bufoff, gbase, voff) do { _Pragma("unroll") for (int _i = 0; _i < 2; ++_i) \
;         __builtin_amdgcn_global_load_lds((const unsigned*)((const char*)(gbase) + (voff)[_i]), (PG8_LAS unsigned*)(lds + (bufoff) + ldsw + _i * 8192), 16, 0, 0); } while (0)
; #define PG8_LDA(dst, b, h) do { _Pragma("unroll") for (int m = 0; m < 4; ++m) _Pragma("unroll") for (int k = 0; k < 2; ++k) dst[m][k] = *(const PG8_LAS bf16x8*)(lds + PG8_SA(b, h) + aoff + m * 2048 + k * 1024); } while (0)
; #define PG8_LDB(dst, b, h) do { _Pragma("unroll") for (int n = 0; n < 2; ++n) _Pragma("unroll") for (int k = 0; k < 2; ++k) dst[n][k] = *(const PG8_LAS bf16x8*)(lds + PG8_SB(b, h) + boff + n * 2048 + k * 1024); } while (0)
; #define PG8_MMA(ai, bj, At, Bt) do { __builtin_amdgcn_s_setprio(1); _Pragma("unroll") for (int m = 0; m < 4; ++m) _Pragma("unroll") for (int n = 0; n < 2; ++n) _Pragma("unroll") for (int k = 0; k < 2; ++k) \
;         acc[ai][bj][m][n] = __builtin_amdgcn_mfma_f32_16x16x32_bf16(Bt[n][k], At[m][k], acc[ai][bj][m][n], 0, 0, 0); __builtin_amdgcn_s_setprio(0); } while (0)
; #define PG8_WAIT_V(n) asm volatile("s_waitcnt vmcnt(" #n ")" ::: "memory")
; #define PG8_WAIT_L(n) asm volatile("s_waitcnt lgkmcnt(" #n ")" ::: "memory")
; #define PG8_BAR __builtin_amdgcn_s_barrier()
; #define PG8_SCHED __builtin_amdgcn_sched_barrier(0)
; template <class Epi, class Sched, bool ALIGN_EPI = false, bool SP2 = false>
; __device__ __forceinline__ void gemm_phase(PG8_LAS unsigned char* lds, const Gemm g, const Sched& S, const Epi& E) {
;     ...
;             PG8_WAIT_V(8); PG8_WAIT_L(0); PG8_BAR; PG8_MMA(1, 0, At, B0); PG8_MMA(1, 1, At, B1); PG8_BAR; PG8_SCHED;
;             PG8_LDB(B0, 1, 0); PG8_LDB(B1, 1, 1); PG8_SCHED; PG8_LDA(At, 1, 0); PG8_STAGE(PG8_SA(0, 1), a2 + hstep, voffA);
;             PG8_WAIT_V(8); PG8_WAIT_L(0); PG8_BAR; PG8_MMA(0, 0, At, B0); PG8_MMA(0, 1, At, B1); PG8_BAR; PG8_SCHED;
;             PG8_LDA(At, 1, 1); PG8_STAGE(PG8_SB(1, 0), b3, voffB); PG8_STAGE(PG8_SB(1, 1), b3 + hstep, voffB); PG8_STAGE(PG8_SA(1, 0), a3, voffA);
;             PG8_WAIT_V(8); PG8_WAIT_L(0); PG8_BAR; PG8_MMA(1, 0, At, B0); PG8_MMA(1, 1, At, B1); PG8_BAR; PG8_SCHED;
	s_waitcnt lgkmcnt(0)
	v_mfma_f32_16x16x32_bf16 v[62:65], v[142:145], v[174:177], 0
	v_mfma_f32_16x16x32_bf16 v[58:61], v[150:153], v[174:177], 0
	v_mfma_f32_16x16x32_bf16 v[54:57], v[142:145], v[182:185], 0
	v_mfma_f32_16x16x32_bf16 v[50:53], v[150:153], v[182:185], 0
	v_mfma_f32_16x16x32_bf16 v[42:45], v[142:145], v[190:193], 0
	v_mfma_f32_16x16x32_bf16 v[34:37], v[150:153], v[190:193], 0
	v_mfma_f32_16x16x32_bf16 v[26:29], v[142:145], v[202:205], 0
	v_mfma_f32_16x16x32_bf16 v[18:21], v[150:153], v[202:205], 0
	v_mfma_f32_16x16x32_bf16 v[62:65], v[146:149], v[178:181], v[62:65]
	v_mfma_f32_16x16x32_bf16 v[58:61], v[154:157], v[178:181], v[58:61]
	v_mfma_f32_16x16x32_bf16 v[54:57], v[146:149], v[186:189], v[54:57]
	v_mfma_f32_16x16x32_bf16 v[50:53], v[154:157], v[186:189], v[50:53]
	v_mfma_f32_16x16x32_bf16 v[42:45], v[146:149], v[198:201], v[42:45]
	v_mfma_f32_16x16x32_bf16 v[34:37], v[154:157], v[198:201], v[34:37]
	v_mfma_f32_16x16x32_bf16 v[26:29], v[146:149], v[206:209], v[26:29]
	v_mfma_f32_16x16x32_bf16 v[18:21], v[154:157], v[206:209], v[18:21]
	v_mfma_f32_16x16x32_bf16 v[46:49], v[158:161], v[174:177], 0
	v_mfma_f32_16x16x32_bf16 v[38:41], v[166:169], v[174:177], 0
	v_mfma_f32_16x16x32_bf16 v[30:33], v[158:161], v[182:185], 0
	v_mfma_f32_16x16x32_bf16 v[22:25], v[166:169], v[182:185], 0
	v_mfma_f32_16x16x32_bf16 v[14:17], v[158:161], v[190:193], 0
	v_mfma_f32_16x16x32_bf16 v[10:13], v[166:169], v[190:193], 0
	v_mfma_f32_16x16x32_bf16 v[6:9], v[158:161], v[202:205], 0
	v_mfma_f32_16x16x32_bf16 v[2:5], v[166:169], v[202:205], 0
	v_mfma_f32_16x16x32_bf16 v[46:49], v[162:165], v[178:181], v[46:49]
	v_mfma_f32_16x16x32_bf16 v[38:41], v[170:173], v[178:181], v[38:41]
	v_mfma_f32_16x16x32_bf16 v[30:33], v[162:165], v[186:189], v[30:33]
	v_mfma_f32_16x16x32_bf16 v[22:25], v[170:173], v[186:189], v[22:25]
	v_mfma_f32_16x16x32_bf16 v[14:17], v[162:165], v[198:201], v[14:17]
	v_mfma_f32_16x16x32_bf16 v[10:13], v[170:173], v[198:201], v[10:13]
	v_mfma_f32_16x16x32_bf16 v[6:9], v[162:165], v[206:209], v[6:9]
	v_mfma_f32_16x16x32_bf16 v[2:5], v[170:173], v[206:209], v[2:5]
	s_barrier
	s_add_i32 s72, 0, 0x18000
	v_add_u32_e32 v0, s72, v139
	s_add_i32 s73, 0, 0x1c000
	ds_read_b128 v[142:145], v0
	ds_read_b128 v[146:149], v0 offset:1024
	ds_read_b128 v[150:153], v0 offset:2048
	ds_read_b128 v[154:157], v0 offset:3072
	v_add_u32_e32 v0, s73, v139
	ds_read_b128 v[158:161], v0
	ds_read_b128 v[162:165], v0 offset:1024
	ds_read_b128 v[166:169], v0 offset:2048
	ds_read_b128 v[170:173], v0 offset:3072
	s_add_u32 s38, s38, s8
	s_addc_u32 s39, s39, 0
	s_mov_b32 m0, s44
	v_lshl_add_u64 v[222:223], s[38:39], 0, v[132:133]
	ds_read_b128 v[174:177], v141 offset:32768
	ds_read_b128 v[178:181], v141 offset:33792
	ds_read_b128 v[182:185], v141 offset:34816
	ds_read_b128 v[186:189], v141 offset:35840
	ds_read_b128 v[190:193], v141 offset:36864
	ds_read_b128 v[198:201], v141 offset:37888
	ds_read_b128 v[202:205], v141 offset:38912
	ds_read_b128 v[206:209], v141 offset:39936
	global_load_lds_dwordx4 v[222:223], off
	v_lshl_add_u64 v[222:223], s[38:39], 0, v[130:131]
	s_mov_b32 m0, s45
	s_nop 0
	global_load_lds_dwordx4 v[222:223], off
	s_waitcnt vmcnt(8)
	s_waitcnt lgkmcnt(0)
	s_barrier
	s_waitcnt lgkmcnt(0)
	v_mfma_f32_16x16x32_bf16 v[126:129], v[142:145], v[174:177], v[126:129]
	v_mfma_f32_16x16x32_bf16 v[122:125], v[150:153], v[174:177], v[122:125]
	v_mfma_f32_16x16x32_bf16 v[118:121], v[142:145], v[182:185], v[118:121]
	v_mfma_f32_16x16x32_bf16 v[114:117], v[150:153], v[182:185], v[114:117]
	v_mfma_f32_16x16x32_bf16 v[110:113], v[142:145], v[190:193], v[110:113]
	v_mfma_f32_16x16x32_bf16 v[102:105], v[150:153], v[190:193], v[102:105]
	v_mfma_f32_16x16x32_bf16 v[90:93], v[142:145], v[202:205], v[90:93]
	v_mfma_f32_16x16x32_bf16 v[82:85], v[150:153], v[202:205], v[82:85]
	v_mfma_f32_16x16x32_bf16 v[126:129], v[146:149], v[178:181], v[126:129]
	v_mfma_f32_16x16x32_bf16 v[122:125], v[154:157], v[178:181], v[122:125]
	v_mfma_f32_16x16x32_bf16 v[118:121], v[146:149], v[186:189], v[118:121]
	v_mfma_f32_16x16x32_bf16 v[114:117], v[154:157], v[186:189], v[114:117]
	v_mfma_f32_16x16x32_bf16 v[110:113], v[146:149], v[198:201], v[110:113]
	v_mfma_f32_16x16x32_bf16 v[102:105], v[154:157], v[198:201], v[102:105]
	v_mfma_f32_16x16x32_bf16 v[90:93], v[146:149], v[206:209], v[90:93]
	v_mfma_f32_16x16x32_bf16 v[82:85], v[154:157], v[206:209], v[82:85]
	v_mfma_f32_16x16x32_bf16 v[106:109], v[158:161], v[174:177], v[106:109]
	v_mfma_f32_16x16x32_bf16 v[98:101], v[166:169], v[174:177], v[98:101]
	v_mfma_f32_16x16x32_bf16 v[94:97], v[158:161], v[182:185], v[94:97]
	v_mfma_f32_16x16x32_bf16 v[86:89], v[166:169], v[182:185], v[86:89]
	v_mfma_f32_16x16x32_bf16 v[78:81], v[158:161], v[190:193], v[78:81]
	v_mfma_f32_16x16x32_bf16 v[74:77], v[166:169], v[190:193], v[74:77]
	v_mfma_f32_16x16x32_bf16 v[70:73], v[158:161], v[202:205], v[70:73]
	v_mfma_f32_16x16x32_bf16 v[66:69], v[166:169], v[202:205], v[66:69]
	v_mfma_f32_16x16x32_bf16 v[106:109], v[162:165], v[178:181], v[106:109]
	v_mfma_f32_16x16x32_bf16 v[98:101], v[170:173], v[178:181], v[98:101]
	v_mfma_f32_16x16x32_bf16 v[94:97], v[162:165], v[186:189], v[94:97]
	v_mfma_f32_16x16x32_bf16 v[86:89], v[170:173], v[186:189], v[86:89]
	v_mfma_f32_16x16x32_bf16 v[78:81], v[162:165], v[198:201], v[78:81]
	v_mfma_f32_16x16x32_bf16 v[74:77], v[170:173], v[198:201], v[74:77]
	v_mfma_f32_16x16x32_bf16 v[70:73], v[162:165], v[206:209], v[70:73]
	v_mfma_f32_16x16x32_bf16 v[66:69], v[170:173], v[206:209], v[66:69]
	s_barrier
; #define PG8_STAGE(bufoff, gbase, voff) do { _Pragma("unroll") for (int _i = 0; _i < 2; ++_i) \
;         __builtin_amdgcn_global_load_lds((const unsigned*)((const char*)(gbase) + (voff)[_i]), (PG8_LAS unsigned*)(lds + (bufoff) + ldsw + _i * 8192), 16, 0, 0); } while (0)
; #define PG8_LDA(dst, b, h) do { _Pragma("unroll") for (int m = 0; m < 4; ++m) _Pragma("unroll") for (int k = 0; k < 2; ++k) dst[m][k] = *(const PG8_LAS bf16x8*)(lds + PG8_SA(b, h) + aoff + m * 2048 + k * 1024); } while (0)
; #define PG8_LDB(dst, b, h) do { _Pragma("unroll") for (int n = 0; n < 2; ++n) _Pragma("unroll") for (int k = 0; k < 2; ++k) dst[n][k] = *(const PG8_LAS bf16x8*)(lds + PG8_SB(b, h) + boff + n * 2048 + k * 1024); } while (0)
; #define PG8_MMA(ai, bj, At, Bt) do { __builtin_amdgcn_s_setprio(1); _Pragma("unroll") for (int m = 0; m < 4; ++m) _Pragma("unroll") for (int n = 0; n < 2; ++n) _Pragma("unroll") for (int k = 0; k < 2; ++k) \
;         acc[ai][bj][m][n] = __builtin_amdgcn_mfma_f32_16x16x32_bf16(Bt[n][k], At[m][k], acc[ai][bj][m][n], 0, 0, 0); __builtin_amdgcn_s_setprio(0); } while (0)
; #define PG8_WAIT_V(n) asm volatile("s_waitcnt vmcnt(" #n ")" ::: "memory")
; #define PG8_WAIT_L(n) asm volatile("s_waitcnt lgkmcnt(" #n ")" ::: "memory")
; #define PG8_BAR __builtin_amdgcn_s_barrier()
; #define PG8_SCHED __builtin_amdgcn_sched_barrier(0)
; template <class Epi, class Sched, bool ALIGN_EPI = false, bool SP2 = false>
; __device__ __forceinline__ void gemm_phase(PG8_LAS unsigned char* lds, const Gemm g, const Sched& S, const Epi& E) {
;     ...
;             PG8_LDB(B0, 1, 0); PG8_LDB(B1, 1, 1); PG8_SCHED; PG8_LDA(At, 1, 0); PG8_STAGE(PG8_SA(0, 1), a2 + hstep, voffA);
;             PG8_WAIT_V(8); PG8_WAIT_L(0); PG8_BAR; PG8_MMA(0, 0, At, B0); PG8_MMA(0, 1, At, B1); PG8_BAR; PG8_SCHED;
;             PG8_LDA(At, 1, 1); PG8_STAGE(PG8_SB(1, 0), b3, voffB); PG8_STAGE(PG8_SB(1, 1), b3 + hstep, voffB); PG8_STAGE(PG8_SA(1, 0), a3, voffA);
;             PG8_WAIT_V(8); PG8_WAIT_L(0); PG8_BAR; PG8_MMA(1, 0, At, B0); PG8_MMA(1, 1, At, B1); PG8_BAR; PG8_SCHED;
	s_add_i32 s38, s72, s41
	v_lshl_add_u64 v[210:211], v[210:211], 0, s[58:59]
	s_mov_b32 m0, s38
	ds_read_b128 v[174:177], v141 offset:49152
	ds_read_b128 v[178:181], v141 offset:50176
	ds_read_b128 v[182:185], v141 offset:51200
	ds_read_b128 v[186:189], v141 offset:52224
	ds_read_b128 v[190:193], v141 offset:53248
	ds_read_b128 v[198:201], v141 offset:54272
	ds_read_b128 v[202:205], v141 offset:55296
	ds_read_b128 v[206:209], v141 offset:56320
	global_load_lds_dwordx4 v[210:211], off
	v_lshl_add_u64 v[210:211], v[212:213], 0, s[58:59]
	s_add_i32 m0, s38, 0x2000
	s_add_i32 s38, s73, s41
	global_load_lds_dwordx4 v[210:211], off
	v_lshl_add_u64 v[210:211], v[214:215], 0, s[58:59]
	s_mov_b32 m0, s38
	s_nop 0
	global_load_lds_dwordx4 v[210:211], off
	v_lshl_add_u64 v[210:211], v[216:217], 0, s[58:59]
	s_add_i32 m0, s38, 0x2000
	s_nop 0
	global_load_lds_dwordx4 v[210:211], off
	v_lshl_add_u64 v[210:211], v[218:219], 0, s[58:59]
	s_mov_b32 m0, s50
	s_nop 0
	global_load_lds_dwordx4 v[210:211], off
	v_lshl_add_u64 v[210:211], v[220:221], 0, s[58:59]
	s_mov_b32 m0, s51
	s_nop 0
	global_load_lds_dwordx4 v[210:211], off
	s_waitcnt vmcnt(8)
	s_waitcnt lgkmcnt(0)
	s_barrier
	s_waitcnt lgkmcnt(0)
	v_mfma_f32_16x16x32_bf16 v[62:65], v[142:145], v[174:177], v[62:65]
	v_mfma_f32_16x16x32_bf16 v[58:61], v[150:153], v[174:177], v[58:61]
	v_mfma_f32_16x16x32_bf16 v[54:57], v[142:145], v[182:185], v[54:57]
	v_mfma_f32_16x16x32_bf16 v[50:53], v[150:153], v[182:185], v[50:53]
	v_mfma_f32_16x16x32_bf16 v[42:45], v[142:145], v[190:193], v[42:45]
	v_mfma_f32_16x16x32_bf16 v[34:37], v[150:153], v[190:193], v[34:37]
	v_mfma_f32_16x16x32_bf16 v[26:29], v[142:145], v[202:205], v[26:29]
	v_mfma_f32_16x16x32_bf16 v[18:21], v[150:153], v[202:205], v[18:21]
	v_mfma_f32_16x16x32_bf16 v[62:65], v[146:149], v[178:181], v[62:65]
	v_mfma_f32_16x16x32_bf16 v[58:61], v[154:157], v[178:181], v[58:61]
	v_mfma_f32_16x16x32_bf16 v[54:57], v[146:149], v[186:189], v[54:57]
	v_mfma_f32_16x16x32_bf16 v[50:53], v[154:157], v[186:189], v[50:53]
	v_mfma_f32_16x16x32_bf16 v[42:45], v[146:149], v[198:201], v[42:45]
	v_mfma_f32_16x16x32_bf16 v[34:37], v[154:157], v[198:201], v[34:37]
	v_mfma_f32_16x16x32_bf16 v[26:29], v[146:149], v[206:209], v[26:29]
	v_mfma_f32_16x16x32_bf16 v[18:21], v[154:157], v[206:209], v[18:21]
	v_mfma_f32_16x16x32_bf16 v[46:49], v[158:161], v[174:177], v[46:49]
	v_mfma_f32_16x16x32_bf16 v[38:41], v[166:169], v[174:177], v[38:41]
	v_mfma_f32_16x16x32_bf16 v[30:33], v[158:161], v[182:185], v[30:33]
	v_mfma_f32_16x16x32_bf16 v[22:25], v[166:169], v[182:185], v[22:25]
	v_mfma_f32_16x16x32_bf16 v[14:17], v[158:161], v[190:193], v[14:17]
	v_mfma_f32_16x16x32_bf16 v[10:13], v[166:169], v[190:193], v[10:13]
	v_mfma_f32_16x16x32_bf16 v[6:9], v[158:161], v[202:205], v[6:9]
	v_mfma_f32_16x16x32_bf16 v[2:5], v[166:169], v[202:205], v[2:5]
	v_mfma_f32_16x16x32_bf16 v[46:49], v[162:165], v[178:181], v[46:49]
	v_mfma_f32_16x16x32_bf16 v[38:41], v[170:173], v[178:181], v[38:41]
	v_mfma_f32_16x16x32_bf16 v[30:33], v[162:165], v[186:189], v[30:33]
	v_mfma_f32_16x16x32_bf16 v[22:25], v[170:173], v[186:189], v[22:25]
	v_mfma_f32_16x16x32_bf16 v[14:17], v[162:165], v[198:201], v[14:17]
	v_mfma_f32_16x16x32_bf16 v[10:13], v[170:173], v[198:201], v[10:13]
	v_mfma_f32_16x16x32_bf16 v[6:9], v[162:165], v[206:209], v[6:9]
	v_mfma_f32_16x16x32_bf16 v[2:5], v[170:173], v[206:209], v[2:5]
	s_barrier
	s_add_u32 s30, s30, 0x100
	s_addc_u32 s31, s31, 0
	s_add_u32 s65, s65, 0x100
	s_addc_u32 s86, s86, 0
	v_readfirstlane_b32 s98, v195
	s_cmp_lt_u32 s98, 0x100
	s_cbranch_scc0 .Lprio_skip_833
	s_setprio 1
.Lprio_skip_833:
	s_cmp_ge_u32 s87, s4
	s_mov_b32 s38, s87
	s_cbranch_scc1 .Lpeel_done_833

; #define PG8_STAGE(bufoff, gbase, voff) do { _Pragma("unroll") for (int _i = 0; _i < 2; ++_i) \
;         __builtin_amdgcn_global_load_lds((const unsigned*)((const char*)(gbase) + (voff)[_i]), (PG8_LAS unsigned*)(lds + (bufoff) + ldsw + _i * 8192), 16, 0, 0); } while (0)
; #define PG8_LDA(dst, b, h) do { _Pragma("unroll") for (int m = 0; m < 4; ++m) _Pragma("unroll") for (int k = 0; k < 2; ++k) dst[m][k] = *(const PG8_LAS bf16x8*)(lds + PG8_SA(b, h) + aoff + m * 2048 + k * 1024); } while (0)
; #define PG8_LDB(dst, b, h) do { _Pragma("unroll") for (int n = 0; n < 2; ++n) _Pragma("unroll") for (int k = 0; k < 2; ++k) dst[n][k] = *(const PG8_LAS bf16x8*)(lds + PG8_SB(b, h) + boff + n * 2048 + k * 1024); } while (0)
; #define PG8_WAIT_V(n) asm volatile("s_waitcnt vmcnt(" #n ")" ::: "memory")
; #define PG8_WAIT_L(n) asm volatile("s_waitcnt lgkmcnt(" #n ")" ::: "memory")
; #define PG8_BAR __builtin_amdgcn_s_barrier()
; #define PG8_SCHED __builtin_amdgcn_sched_barrier(0)
; template <class Epi, class Sched, bool ALIGN_EPI = false, bool SP2 = false>
; __device__ __forceinline__ void gemm_phase(PG8_LAS unsigned char* lds, const Gemm g, const Sched& S, const Epi& E) {
;     ...
;         const char* nA = has_next ? (const char*)g.A + (size_t)nxt.pm * tstep : cA; const char* nB = has_next ? (const char*)g.Bt + (size_t)nxt.pn * tstep : cB;
;         for (int t = 0; t < nt; t += 2) {
;             const bool last = (t == nt - 2);
;             const char* a1 = cA + (size_t)(t + 1) * kstep;
;             const char* a2 = last ? nA : cA + (size_t)(t + 2) * kstep; const char* b2 = last ? nB : cB + (size_t)(t + 2) * kstep;
;             const char* a3 = a2 + kstep; const char* b3 = b2 + kstep;
;             if (last && has_next) S.a_ready(nxt);
;             if constexpr (SP2) {
;             PG8_LDB(B0, 0, 0); PG8_LDB(B1, 0, 1); PG8_SCHED; PG8_LDA(At, 0, 0); PG8_STAGE(PG8_SA(1, 1), a1 + hstep, voffA);
;             PG8_WAIT_V(8); PG8_WAIT_L(0); PG8_BAR; PG8_MMA(0, 0, At, B0); PG8_MMA(0, 1, At, B1); PG8_BAR; PG8_SCHED;
;             PG8_LDA(At, 0, 1); PG8_STAGE(PG8_SB(0, 0), b2, voffB); PG8_STAGE(PG8_SB(0, 1), b2 + hstep, voffB); PG8_STAGE(PG8_SA(0, 0), a2, voffA);
;             PG8_WAIT_V(8); PG8_WAIT_L(0); PG8_BAR; PG8_MMA(1, 0, At, B0); PG8_MMA(1, 1, At, B1); PG8_BAR; PG8_SCHED;
.LBB0_1179:
	s_ashr_i32 s21, s20, 31
	s_lshl_b64 s[30:31], s[20:21], 19
	s_add_u32 s30, s77, s30
	s_addc_u32 s31, s26, s31
	s_and_b64 s[38:39], s[6:7], exec
	s_cselect_b32 s21, s31, s43
	s_cselect_b32 s29, s30, s42
	s_ashr_i32 s19, s18, 31
	s_lshl_b64 s[38:39], s[18:19], 19
	s_add_u32 s38, s22, s38
	s_addc_u32 s39, s23, s39
	s_and_b64 s[46:47], s[6:7], exec
	s_cselect_b32 s19, s39, s45
	s_cselect_b32 s41, s38, s44
	s_add_u32 s42, s42, 0x40080
	s_addc_u32 s43, s43, 0
	s_add_u32 s73, s44, 0x100
	s_addc_u32 s78, s45, 0
	s_mov_b32 s79, -2
	s_add_u32 s44, s42, 0xfffc0080
	s_addc_u32 s45, s43, -1
	s_add_i32 s86, 0, 0x10000
	s_cmp_eq_u32 s79, 12
	s_cselect_b32 s47, s21, s45
	s_cselect_b32 s46, s29, s44
	v_add_u32_e32 v0, s86, v145
	s_cselect_b32 s45, s19, s78
	s_cselect_b32 s44, s41, s73
	s_add_i32 s93, 0, 0x14000
	ds_read_b128 v[148:151], v0
	ds_read_b128 v[152:155], v0 offset:1024
	ds_read_b128 v[156:159], v0 offset:2048
	ds_read_b128 v[160:163], v0 offset:3072
	v_add_u32_e32 v0, s93, v145
	ds_read_b128 v[164:167], v0
	ds_read_b128 v[168:171], v0 offset:1024
	ds_read_b128 v[172:175], v0 offset:2048
	ds_read_b128 v[176:179], v0 offset:3072
	v_lshl_add_u64 v[142:143], s[42:43], 0, v[138:139]
	s_add_i32 m0, s49, 0xc000
	ds_read_b128 v[180:183], v147
	ds_read_b128 v[184:187], v147 offset:1024
	ds_read_b128 v[188:191], v147 offset:2048
	ds_read_b128 v[198:201], v147 offset:3072
	ds_read_b128 v[202:205], v147 offset:4096
	ds_read_b128 v[206:209], v147 offset:5120
	ds_read_b128 v[210:213], v147 offset:6144
	ds_read_b128 v[214:217], v147 offset:7168
	global_load_lds_dwordx4 v[142:143], off
	v_lshl_add_u64 v[142:143], s[42:43], 0, v[140:141]
	s_add_i32 m0, s49, 0xe000
	s_nop 0
	global_load_lds_dwordx4 v[142:143], off
	s_waitcnt vmcnt(8)
	s_waitcnt lgkmcnt(0)
	s_barrier
	s_waitcnt lgkmcnt(0)
	v_mfma_f32_16x16x32_bf16 v[126:129], v[148:151], v[180:183], 0
	v_mfma_f32_16x16x32_bf16 v[118:121], v[156:159], v[180:183], 0
	v_mfma_f32_16x16x32_bf16 v[110:113], v[148:151], v[188:191], 0
	v_mfma_f32_16x16x32_bf16 v[102:105], v[156:159], v[188:191], 0
	v_mfma_f32_16x16x32_bf16 v[94:97], v[148:151], v[202:205], 0
	v_mfma_f32_16x16x32_bf16 v[86:89], v[156:159], v[202:205], 0
	v_mfma_f32_16x16x32_bf16 v[78:81], v[148:151], v[210:213], 0
	v_mfma_f32_16x16x32_bf16 v[70:73], v[156:159], v[210:213], 0
	v_mfma_f32_16x16x32_bf16 v[126:129], v[152:155], v[184:187], v[126:129]
	v_mfma_f32_16x16x32_bf16 v[118:121], v[160:163], v[184:187], v[118:121]
	v_mfma_f32_16x16x32_bf16 v[110:113], v[152:155], v[198:201], v[110:113]
	v_mfma_f32_16x16x32_bf16 v[102:105], v[160:163], v[198:201], v[102:105]
	v_mfma_f32_16x16x32_bf16 v[94:97], v[152:155], v[206:209], v[94:97]
	v_mfma_f32_16x16x32_bf16 v[86:89], v[160:163], v[206:209], v[86:89]
	v_mfma_f32_16x16x32_bf16 v[78:81], v[152:155], v[214:217], v[78:81]
	v_mfma_f32_16x16x32_bf16 v[70:73], v[160:163], v[214:217], v[70:73]
	v_mfma_f32_16x16x32_bf16 v[122:125], v[164:167], v[180:183], 0
	v_mfma_f32_16x16x32_bf16 v[114:117], v[172:175], v[180:183], 0
	v_mfma_f32_16x16x32_bf16 v[106:109], v[164:167], v[188:191], 0
	v_mfma_f32_16x16x32_bf16 v[98:101], v[172:175], v[188:191], 0
	v_mfma_f32_16x16x32_bf16 v[90:93], v[164:167], v[202:205], 0
	v_mfma_f32_16x16x32_bf16 v[82:85], v[172:175], v[202:205], 0
	v_mfma_f32_16x16x32_bf16 v[74:77], v[164:167], v[210:213], 0
	v_mfma_f32_16x16x32_bf16 v[66:69], v[172:175], v[210:213], 0
	v_mfma_f32_16x16x32_bf16 v[122:125], v[168:171], v[184:187], v[122:125]
	v_mfma_f32_16x16x32_bf16 v[114:117], v[176:179], v[184:187], v[114:117]
	v_mfma_f32_16x16x32_bf16 v[106:109], v[168:171], v[198:201], v[106:109]
	v_mfma_f32_16x16x32_bf16 v[98:101], v[176:179], v[198:201], v[98:101]
	v_mfma_f32_16x16x32_bf16 v[90:93], v[168:171], v[206:209], v[90:93]
	v_mfma_f32_16x16x32_bf16 v[82:85], v[176:179], v[206:209], v[82:85]
	v_mfma_f32_16x16x32_bf16 v[74:77], v[168:171], v[214:217], v[74:77]
	v_mfma_f32_16x16x32_bf16 v[66:69], v[176:179], v[214:217], v[66:69]
	s_barrier
	s_add_i32 s86, s86, s25
	v_lshl_add_u64 v[142:143], s[44:45], 0, v[134:135]
	s_mov_b32 m0, s86
	ds_read_b128 v[180:183], v147 offset:16384
	ds_read_b128 v[184:187], v147 offset:17408
	ds_read_b128 v[188:191], v147 offset:18432
	ds_read_b128 v[198:201], v147 offset:19456
	ds_read_b128 v[202:205], v147 offset:20480
	ds_read_b128 v[206:209], v147 offset:21504
	ds_read_b128 v[210:213], v147 offset:22528
	ds_read_b128 v[214:217], v147 offset:23552
	global_load_lds_dwordx4 v[142:143], off
	s_add_i32 m0, s86, 0x2000
	s_add_u32 s86, s44, 0x40000
	v_lshl_add_u64 v[192:193], s[44:45], 0, v[130:131]
	s_addc_u32 s87, s45, 0
	s_add_i32 s93, s93, s25
	global_load_lds_dwordx4 v[192:193], off
	v_lshl_add_u64 v[218:219], s[86:87], 0, v[134:135]
	s_mov_b32 m0, s93
	v_lshl_add_u64 v[220:221], s[46:47], 0, v[132:133]
	global_load_lds_dwordx4 v[218:219], off
	v_lshl_add_u64 v[218:219], s[86:87], 0, v[130:131]
	s_add_i32 m0, s93, 0x2000
	s_nop 0
	global_load_lds_dwordx4 v[218:219], off
	v_lshl_add_u64 v[218:219], s[46:47], 0, v[136:137]
	s_mov_b32 m0, s49
	s_nop 0
	global_load_lds_dwordx4 v[218:219], off
	s_mov_b32 m0, s50
	s_nop 0
	global_load_lds_dwordx4 v[220:221], off
	s_waitcnt vmcnt(8)
	s_waitcnt lgkmcnt(0)
	s_barrier
; #define PG8_STAGE(bufoff, gbase, voff) do { _Pragma("unroll") for (int _i = 0; _i < 2; ++_i) \
;         __builtin_amdgcn_global_load_lds((const unsigned*)((const char*)(gbase) + (voff)[_i]), (PG8_LAS unsigned*)(lds + (bufoff) + ldsw + _i * 8192), 16, 0, 0); } while (0)
; #define PG8_LDA(dst, b, h) do { _Pragma("unroll") for (int m = 0; m < 4; ++m) _Pragma("unroll") for (int k = 0; k < 2; ++k) dst[m][k] = *(const PG8_LAS bf16x8*)(lds + PG8_SA(b, h) + aoff + m * 2048 + k * 1024); } while (0)
; #define PG8_LDB(dst, b, h) do { _Pragma("unroll") for (int n = 0; n < 2; ++n) _Pragma("unroll") for (int k = 0; k < 2; ++k) dst[n][k] = *(const PG8_LAS bf16x8*)(lds + PG8_SB(b, h) + boff + n * 2048 + k * 1024); } while (0)
; #define PG8_MMA(ai, bj, At, Bt) do { __builtin_amdgcn_s_setprio(1); _Pragma("unroll") for (int m = 0; m < 4; ++m) _Pragma("unroll") for (int n = 0; n < 2; ++n) _Pragma("unroll") for (int k = 0; k < 2; ++k) \
;         acc[ai][bj][m][n] = __builtin_amdgcn_mfma_f32_16x16x32_bf16(Bt[n][k], At[m][k], acc[ai][bj][m][n], 0, 0, 0); __builtin_amdgcn_s_setprio(0); } while (0)
; #define PG8_WAIT_V(n) asm volatile("s_waitcnt vmcnt(" #n ")" ::: "memory")
; #define PG8_WAIT_L(n) asm volatile("s_waitcnt lgkmcnt(" #n ")" ::: "memory")
; #define PG8_BAR __builtin_amdgcn_s_barrier()
; #define PG8_SCHED __builtin_amdgcn_sched_barrier(0)
; template <class Epi, class Sched, bool ALIGN_EPI = false, bool SP2 = false>
; __device__ __forceinline__ void gemm_phase(PG8_LAS unsigned char* lds, const Gemm g, const Sched& S, const Epi& E) {
;     ...
;             PG8_WAIT_V(8); PG8_WAIT_L(0); PG8_BAR; PG8_MMA(1, 0, At, B0); PG8_MMA(1, 1, At, B1); PG8_BAR; PG8_SCHED;
;             PG8_LDB(B0, 1, 0); PG8_LDB(B1, 1, 1); PG8_SCHED; PG8_LDA(At, 1, 0); PG8_STAGE(PG8_SA(0, 1), a2 + hstep, voffA);
;             PG8_WAIT_V(8); PG8_WAIT_L(0); PG8_BAR; PG8_MMA(0, 0, At, B0); PG8_MMA(0, 1, At, B1); PG8_BAR; PG8_SCHED;
;             PG8_LDA(At, 1, 1); PG8_STAGE(PG8_SB(1, 0), b3, voffB); PG8_STAGE(PG8_SB(1, 1), b3 + hstep, voffB); PG8_STAGE(PG8_SA(1, 0), a3, voffA);
;             PG8_WAIT_V(8); PG8_WAIT_L(0); PG8_BAR; PG8_MMA(1, 0, At, B0); PG8_MMA(1, 1, At, B1); PG8_BAR; PG8_SCHED;
	s_waitcnt lgkmcnt(0)
	v_mfma_f32_16x16x32_bf16 v[62:65], v[148:151], v[180:183], 0
	v_mfma_f32_16x16x32_bf16 v[54:57], v[156:159], v[180:183], 0
	v_mfma_f32_16x16x32_bf16 v[46:49], v[148:151], v[188:191], 0
	v_mfma_f32_16x16x32_bf16 v[38:41], v[156:159], v[188:191], 0
	v_mfma_f32_16x16x32_bf16 v[30:33], v[148:151], v[202:205], 0
	v_mfma_f32_16x16x32_bf16 v[22:25], v[156:159], v[202:205], 0
	v_mfma_f32_16x16x32_bf16 v[14:17], v[148:151], v[210:213], 0
	v_mfma_f32_16x16x32_bf16 v[6:9], v[156:159], v[210:213], 0
	v_mfma_f32_16x16x32_bf16 v[62:65], v[152:155], v[184:187], v[62:65]
	v_mfma_f32_16x16x32_bf16 v[54:57], v[160:163], v[184:187], v[54:57]
	v_mfma_f32_16x16x32_bf16 v[46:49], v[152:155], v[198:201], v[46:49]
	v_mfma_f32_16x16x32_bf16 v[38:41], v[160:163], v[198:201], v[38:41]
	v_mfma_f32_16x16x32_bf16 v[30:33], v[152:155], v[206:209], v[30:33]
	v_mfma_f32_16x16x32_bf16 v[22:25], v[160:163], v[206:209], v[22:25]
	v_mfma_f32_16x16x32_bf16 v[14:17], v[152:155], v[214:217], v[14:17]
	v_mfma_f32_16x16x32_bf16 v[6:9], v[160:163], v[214:217], v[6:9]
	v_mfma_f32_16x16x32_bf16 v[58:61], v[164:167], v[180:183], 0
	v_mfma_f32_16x16x32_bf16 v[50:53], v[172:175], v[180:183], 0
	v_mfma_f32_16x16x32_bf16 v[42:45], v[164:167], v[188:191], 0
	v_mfma_f32_16x16x32_bf16 v[34:37], v[172:175], v[188:191], 0
	v_mfma_f32_16x16x32_bf16 v[26:29], v[164:167], v[202:205], 0
	v_mfma_f32_16x16x32_bf16 v[18:21], v[172:175], v[202:205], 0
	v_mfma_f32_16x16x32_bf16 v[10:13], v[164:167], v[210:213], 0
	v_mfma_f32_16x16x32_bf16 v[2:5], v[172:175], v[210:213], 0
	v_mfma_f32_16x16x32_bf16 v[58:61], v[168:171], v[184:187], v[58:61]
	v_mfma_f32_16x16x32_bf16 v[50:53], v[176:179], v[184:187], v[50:53]
	v_mfma_f32_16x16x32_bf16 v[42:45], v[168:171], v[198:201], v[42:45]
	v_mfma_f32_16x16x32_bf16 v[34:37], v[176:179], v[198:201], v[34:37]
	v_mfma_f32_16x16x32_bf16 v[26:29], v[168:171], v[206:209], v[26:29]
	v_mfma_f32_16x16x32_bf16 v[18:21], v[176:179], v[206:209], v[18:21]
	v_mfma_f32_16x16x32_bf16 v[10:13], v[168:171], v[214:217], v[10:13]
	v_mfma_f32_16x16x32_bf16 v[2:5], v[176:179], v[214:217], v[2:5]
	s_barrier
	s_add_i32 s86, 0, 0x18000
	v_add_u32_e32 v0, s86, v145
	s_add_i32 s87, 0, 0x1c000
	ds_read_b128 v[148:151], v0
	ds_read_b128 v[152:155], v0 offset:1024
	ds_read_b128 v[156:159], v0 offset:2048
	ds_read_b128 v[160:163], v0 offset:3072
	v_add_u32_e32 v0, s87, v145
	ds_read_b128 v[164:167], v0
	ds_read_b128 v[168:171], v0 offset:1024
	ds_read_b128 v[172:175], v0 offset:2048
	ds_read_b128 v[176:179], v0 offset:3072
	s_add_u32 s46, s46, 0x40000
	s_addc_u32 s47, s47, 0
	s_mov_b32 m0, s51
	v_lshl_add_u64 v[222:223], s[46:47], 0, v[136:137]
	ds_read_b128 v[180:183], v147 offset:32768
	ds_read_b128 v[184:187], v147 offset:33792
	ds_read_b128 v[188:191], v147 offset:34816
	ds_read_b128 v[198:201], v147 offset:35840
	ds_read_b128 v[202:205], v147 offset:36864
	ds_read_b128 v[206:209], v147 offset:37888
	ds_read_b128 v[210:213], v147 offset:38912
	ds_read_b128 v[214:217], v147 offset:39936
	global_load_lds_dwordx4 v[222:223], off
	v_lshl_add_u64 v[222:223], s[46:47], 0, v[132:133]
	s_mov_b32 m0, s54
	s_nop 0
	global_load_lds_dwordx4 v[222:223], off
	s_waitcnt vmcnt(8)
	s_waitcnt lgkmcnt(0)
	s_barrier
	s_waitcnt lgkmcnt(0)
	v_mfma_f32_16x16x32_bf16 v[126:129], v[148:151], v[180:183], v[126:129]
	v_mfma_f32_16x16x32_bf16 v[118:121], v[156:159], v[180:183], v[118:121]
	v_mfma_f32_16x16x32_bf16 v[110:113], v[148:151], v[188:191], v[110:113]
	v_mfma_f32_16x16x32_bf16 v[102:105], v[156:159], v[188:191], v[102:105]
	v_mfma_f32_16x16x32_bf16 v[94:97], v[148:151], v[202:205], v[94:97]
	v_mfma_f32_16x16x32_bf16 v[86:89], v[156:159], v[202:205], v[86:89]
	v_mfma_f32_16x16x32_bf16 v[78:81], v[148:151], v[210:213], v[78:81]
	v_mfma_f32_16x16x32_bf16 v[70:73], v[156:159], v[210:213], v[70:73]
	v_mfma_f32_16x16x32_bf16 v[126:129], v[152:155], v[184:187], v[126:129]
	v_mfma_f32_16x16x32_bf16 v[118:121], v[160:163], v[184:187], v[118:121]
	v_mfma_f32_16x16x32_bf16 v[110:113], v[152:155], v[198:201], v[110:113]
	v_mfma_f32_16x16x32_bf16 v[102:105], v[160:163], v[198:201], v[102:105]
	v_mfma_f32_16x16x32_bf16 v[94:97], v[152:155], v[206:209], v[94:97]
	v_mfma_f32_16x16x32_bf16 v[86:89], v[160:163], v[206:209], v[86:89]
	v_mfma_f32_16x16x32_bf16 v[78:81], v[152:155], v[214:217], v[78:81]
	v_mfma_f32_16x16x32_bf16 v[70:73], v[160:163], v[214:217], v[70:73]
	v_mfma_f32_16x16x32_bf16 v[122:125], v[164:167], v[180:183], v[122:125]
	v_mfma_f32_16x16x32_bf16 v[114:117], v[172:175], v[180:183], v[114:117]
	v_mfma_f32_16x16x32_bf16 v[106:109], v[164:167], v[188:191], v[106:109]
	v_mfma_f32_16x16x32_bf16 v[98:101], v[172:175], v[188:191], v[98:101]
	v_mfma_f32_16x16x32_bf16 v[90:93], v[164:167], v[202:205], v[90:93]
	v_mfma_f32_16x16x32_bf16 v[82:85], v[172:175], v[202:205], v[82:85]
	v_mfma_f32_16x16x32_bf16 v[74:77], v[164:167], v[210:213], v[74:77]
	v_mfma_f32_16x16x32_bf16 v[66:69], v[172:175], v[210:213], v[66:69]
	v_mfma_f32_16x16x32_bf16 v[122:125], v[168:171], v[184:187], v[122:125]
	v_mfma_f32_16x16x32_bf16 v[114:117], v[176:179], v[184:187], v[114:117]
	v_mfma_f32_16x16x32_bf16 v[106:109], v[168:171], v[198:201], v[106:109]
	v_mfma_f32_16x16x32_bf16 v[98:101], v[176:179], v[198:201], v[98:101]
	v_mfma_f32_16x16x32_bf16 v[90:93], v[168:171], v[206:209], v[90:93]
	v_mfma_f32_16x16x32_bf16 v[82:85], v[176:179], v[206:209], v[82:85]
	v_mfma_f32_16x16x32_bf16 v[74:77], v[168:171], v[214:217], v[74:77]
	v_mfma_f32_16x16x32_bf16 v[66:69], v[176:179], v[214:217], v[66:69]
	s_barrier
; #define PG8_STAGE(bufoff, gbase, voff) do { _Pragma("unroll") for (int _i = 0; _i < 2; ++_i) \
;         __builtin_amdgcn_global_load_lds((const unsigned*)((const char*)(gbase) + (voff)[_i]), (PG8_LAS unsigned*)(lds + (bufoff) + ldsw + _i * 8192), 16, 0, 0); } while (0)
; #define PG8_LDA(dst, b, h) do { _Pragma("unroll") for (int m = 0; m < 4; ++m) _Pragma("unroll") for (int k = 0; k < 2; ++k) dst[m][k] = *(const PG8_LAS bf16x8*)(lds + PG8_SA(b, h) + aoff + m * 2048 + k * 1024); } while (0)
; #define PG8_LDB(dst, b, h) do { _Pragma("unroll") for (int n = 0; n < 2; ++n) _Pragma("unroll") for (int k = 0; k < 2; ++k) dst[n][k] = *(const PG8_LAS bf16x8*)(lds + PG8_SB(b, h) + boff + n * 2048 + k * 1024); } while (0)
; #define PG8_MMA(ai, bj, At, Bt) do { __builtin_amdgcn_s_setprio(1); _Pragma("unroll") for (int m = 0; m < 4; ++m) _Pragma("unroll") for (int n = 0; n < 2; ++n) _Pragma("unroll") for (int k = 0; k < 2; ++k) \
;         acc[ai][bj][m][n] = __builtin_amdgcn_mfma_f32_16x16x32_bf16(Bt[n][k], At[m][k], acc[ai][bj][m][n], 0, 0, 0); __builtin_amdgcn_s_setprio(0); } while (0)
; #define PG8_WAIT_V(n) asm volatile("s_waitcnt vmcnt(" #n ")" ::: "memory")
; #define PG8_WAIT_L(n) asm volatile("s_waitcnt lgkmcnt(" #n ")" ::: "memory")
; #define PG8_BAR __builtin_amdgcn_s_barrier()
; #define PG8_SCHED __builtin_amdgcn_sched_barrier(0)
; template <class Epi, class Sched, bool ALIGN_EPI = false, bool SP2 = false>
; __device__ __forceinline__ void gemm_phase(PG8_LAS unsigned char* lds, const Gemm g, const Sched& S, const Epi& E) {
;     ...
;             PG8_LDB(B0, 1, 0); PG8_LDB(B1, 1, 1); PG8_SCHED; PG8_LDA(At, 1, 0); PG8_STAGE(PG8_SA(0, 1), a2 + hstep, voffA);
;             PG8_WAIT_V(8); PG8_WAIT_L(0); PG8_BAR; PG8_MMA(0, 0, At, B0); PG8_MMA(0, 1, At, B1); PG8_BAR; PG8_SCHED;
;             PG8_LDA(At, 1, 1); PG8_STAGE(PG8_SB(1, 0), b3, voffB); PG8_STAGE(PG8_SB(1, 1), b3 + hstep, voffB); PG8_STAGE(PG8_SA(1, 0), a3, voffA);
;             PG8_WAIT_V(8); PG8_WAIT_L(0); PG8_BAR; PG8_MMA(1, 0, At, B0); PG8_MMA(1, 1, At, B1); PG8_BAR; PG8_SCHED;
	s_add_i32 s46, s86, s25
	v_lshl_add_u64 v[142:143], v[142:143], 0, s[58:59]
	s_mov_b32 m0, s46
	ds_read_b128 v[180:183], v147 offset:49152
	ds_read_b128 v[184:187], v147 offset:50176
	ds_read_b128 v[188:191], v147 offset:51200
	ds_read_b128 v[198:201], v147 offset:52224
	ds_read_b128 v[202:205], v147 offset:53248
	ds_read_b128 v[206:209], v147 offset:54272
	ds_read_b128 v[210:213], v147 offset:55296
	ds_read_b128 v[214:217], v147 offset:56320
	global_load_lds_dwordx4 v[142:143], off
	s_add_i32 m0, s46, 0x2000
	s_add_u32 s44, s44, 0x40080
	v_lshl_add_u64 v[142:143], v[192:193], 0, s[58:59]
	s_addc_u32 s45, s45, 0
	s_add_i32 s46, s87, s25
	global_load_lds_dwordx4 v[142:143], off
	v_lshl_add_u64 v[142:143], s[44:45], 0, v[134:135]
	s_mov_b32 m0, s46
	s_nop 0
	global_load_lds_dwordx4 v[142:143], off
	v_lshl_add_u64 v[142:143], s[44:45], 0, v[130:131]
	s_add_i32 m0, s46, 0x2000
	s_nop 0
	global_load_lds_dwordx4 v[142:143], off
	v_lshl_add_u64 v[142:143], v[218:219], 0, s[58:59]
	s_mov_b32 m0, s55
	s_nop 0
	global_load_lds_dwordx4 v[142:143], off
	v_lshl_add_u64 v[142:143], v[220:221], 0, s[58:59]
	s_mov_b32 m0, s63
	s_nop 0
	global_load_lds_dwordx4 v[142:143], off
	s_waitcnt vmcnt(8)
	s_waitcnt lgkmcnt(0)
	s_barrier
	s_waitcnt lgkmcnt(0)
	v_mfma_f32_16x16x32_bf16 v[62:65], v[148:151], v[180:183], v[62:65]
	v_mfma_f32_16x16x32_bf16 v[54:57], v[156:159], v[180:183], v[54:57]
	v_mfma_f32_16x16x32_bf16 v[46:49], v[148:151], v[188:191], v[46:49]
	v_mfma_f32_16x16x32_bf16 v[38:41], v[156:159], v[188:191], v[38:41]
	v_mfma_f32_16x16x32_bf16 v[30:33], v[148:151], v[202:205], v[30:33]
	v_mfma_f32_16x16x32_bf16 v[22:25], v[156:159], v[202:205], v[22:25]
	v_mfma_f32_16x16x32_bf16 v[14:17], v[148:151], v[210:213], v[14:17]
	v_mfma_f32_16x16x32_bf16 v[6:9], v[156:159], v[210:213], v[6:9]
	v_mfma_f32_16x16x32_bf16 v[62:65], v[152:155], v[184:187], v[62:65]
	v_mfma_f32_16x16x32_bf16 v[54:57], v[160:163], v[184:187], v[54:57]
	v_mfma_f32_16x16x32_bf16 v[46:49], v[152:155], v[198:201], v[46:49]
	v_mfma_f32_16x16x32_bf16 v[38:41], v[160:163], v[198:201], v[38:41]
	v_mfma_f32_16x16x32_bf16 v[30:33], v[152:155], v[206:209], v[30:33]
	v_mfma_f32_16x16x32_bf16 v[22:25], v[160:163], v[206:209], v[22:25]
	v_mfma_f32_16x16x32_bf16 v[14:17], v[152:155], v[214:217], v[14:17]
	v_mfma_f32_16x16x32_bf16 v[6:9], v[160:163], v[214:217], v[6:9]
	v_mfma_f32_16x16x32_bf16 v[58:61], v[164:167], v[180:183], v[58:61]
	v_mfma_f32_16x16x32_bf16 v[50:53], v[172:175], v[180:183], v[50:53]
	v_mfma_f32_16x16x32_bf16 v[42:45], v[164:167], v[188:191], v[42:45]
	v_mfma_f32_16x16x32_bf16 v[34:37], v[172:175], v[188:191], v[34:37]
	v_mfma_f32_16x16x32_bf16 v[26:29], v[164:167], v[202:205], v[26:29]
	v_mfma_f32_16x16x32_bf16 v[18:21], v[172:175], v[202:205], v[18:21]
	v_mfma_f32_16x16x32_bf16 v[10:13], v[164:167], v[210:213], v[10:13]
	v_mfma_f32_16x16x32_bf16 v[2:5], v[172:175], v[210:213], v[2:5]
	v_mfma_f32_16x16x32_bf16 v[58:61], v[168:171], v[184:187], v[58:61]
	v_mfma_f32_16x16x32_bf16 v[50:53], v[176:179], v[184:187], v[50:53]
	v_mfma_f32_16x16x32_bf16 v[42:45], v[168:171], v[198:201], v[42:45]
	v_mfma_f32_16x16x32_bf16 v[34:37], v[176:179], v[198:201], v[34:37]
	v_mfma_f32_16x16x32_bf16 v[26:29], v[168:171], v[206:209], v[26:29]
	v_mfma_f32_16x16x32_bf16 v[18:21], v[176:179], v[206:209], v[18:21]
	v_mfma_f32_16x16x32_bf16 v[10:13], v[168:171], v[214:217], v[10:13]
	v_mfma_f32_16x16x32_bf16 v[2:5], v[176:179], v[214:217], v[2:5]
	s_barrier
	s_add_i32 s79, s79, 2
	s_add_u32 s42, s42, 0x100
	s_addc_u32 s43, s43, 0
	s_add_u32 s73, s73, 0x100
	s_addc_u32 s78, s78, 0
	v_readfirstlane_b32 s98, v195
	s_cmp_lt_u32 s98, 0x100
	s_cbranch_scc0 .Lprio_skip_1180
	s_setprio 1
.Lprio_skip_1180:
	s_cmp_gt_u32 s79, 13
	s_cbranch_scc1 .Lpeel_done_1180

; __global__ void __launch_bounds__(NTHR, 2) fwd_megakernel(Prm p_unused, int lo, int hi) {
;     ...
;         for (int st = 0; st < 13; ++st) {
.LBB0_1284:
	s_setprio 0
	s_add_i32 s91, s91, 1
	s_cmp_eq_u32 s91, 13
	s_cbranch_scc0 .LBB0_1285
	s_getpc_b64 s[98:99]
